# merge phase: sigmoid via v_exp_f32+v_rcp_f32 (f32) in place of IEEE division sequence
# speedup vs baseline: 1.0880x; 1.0092x over previous
;   const int tid = TIDX, lane = tid & 63, wid = tid >> 6, wr = wid >> 1, wc = wid & 1, r = lane & 31, h = lane >> 5;
;   const int ch = (tid & 7) ^ ((tid >> 4) & 7);
;   unsigned avo[4], bvo[2];
; #pragma unroll
;   for (int i = 0; i < 4; ++i) avo[i] = (unsigned)(((tid >> 3) + 64 * i) * lda * 2 + ch * 16);
; #pragma unroll
;   for (int i = 0; i < 2; ++i) bvo[i] = (unsigned)(((tid >> 3) + 64 * i) * ldb * 2 + ch * 16);
;   const char* Ab = (const char*)A; const char* Bb = (const char*)Bt;
;   char* lw = lds + tid * 16;
;   const int nk = K >> 6;
;   const unsigned swz = (unsigned)((r >> 1) & 7);
;   const unsigned arow_u = (unsigned)((wr * 64 + r) * 128), brow_u = (unsigned)((wc * 64 + r) * 128);
;   const unsigned co0 = ((0u + h) ^ swz) << 4, co1 = ((2u + h) ^ swz) << 4, co2 = ((4u + h) ^ swz) << 4, co3 = ((6u + h) ^ swz) << 4;
;     ...
;   if (PART != 2) {
;     GEMM_ISSUE(0, 0);
;     if (nk > 1) GEMM_ISSUE(1, 1);
;   }
;   if (PART == 1) return;
;   int st = 0;
;   for (int kt = 0; kt < nk; ++kt) {
;     if (kt + 1 < nk) asm volatile("s_waitcnt vmcnt(6)" ::: "memory");
;     else asm volatile("s_waitcnt vmcnt(0)" ::: "memory");
;     __builtin_amdgcn_s_barrier();
;     asm volatile("" ::: "memory");
;     if (kt + 2 < nk) { const int st2 = (st >= 1) ? st - 1 : 2; GEMM_ISSUE(kt + 2, st2); }
;     const char* la = lds + st * STAGE_B;
;     const char* lb = la + 32768;
;     const unsigned sa_u = (unsigned)(size_t)la + arow_u, sb_u = (unsigned)(size_t)lb + brow_u;
;     const unsigned a0 = sa_u + co0, a1 = sa_u + co1, a2 = sa_u + co2, a3 = sa_u + co3;
;     const unsigned b0 = sb_u + co0, b1 = sb_u + co1, b2 = sb_u + co2, b3 = sb_u + co3;
;     {
;       bf16x8 p0, p1, q0, q1, u0, u1, w0, w1;
;       asm volatile(
;         "ds_read_b128 %4, %12\n\tds_read_b128 %5, %12 offset:4096\n\tds_read_b128 %6, %16\n\tds_read_b128 %7, %16 offset:4096\n\t"
;         "ds_read_b128 %8, %13\n\tds_read_b128 %9, %13 offset:4096\n\tds_read_b128 %10, %17\n\tds_read_b128 %11, %17 offset:4096\n\t"
;         "s_waitcnt lgkmcnt(4)\n\t"
;         "v_mfma_f32_32x32x16_bf16 %0, %4, %6, %0\n\tv_mfma_f32_32x32x16_bf16 %1, %4, %7, %1\n\tv_mfma_f32_32x32x16_bf16 %2, %5, %6, %2\n\tv_mfma_f32_32x32x16_bf16 %3, %5, %7, %3\n\t"
;         "ds_read_b128 %4, %14\n\tds_read_b128 %5, %14 offset:4096\n\tds_read_b128 %6, %18\n\tds_read_b128 %7, %18 offset:4096\n\t"
;         "s_waitcnt lgkmcnt(4)\n\t"
.LBB0_106:
	v_and_b32_e32 v164, 31, v129
	v_bfe_u32 v165, v129, 5, 1
	v_lshrrev_b32_e32 v166, 6, v129
	v_bfe_u32 v168, v129, 1, 3
	v_lshrrev_b32_e32 v167, 1, v166
	v_and_b32_e32 v166, 1, v166
	v_xor_b32_e32 v165, v165, v168
	v_lshl_add_u32 v167, v167, 6, v164
	v_lshl_add_u32 v166, v166, 6, v164
	v_lshlrev_b32_e32 v165, 4, v165
	v_lshlrev_b32_e32 v167, 7, v167
	v_lshlrev_b32_e32 v166, 7, v166
	v_add_u32_e32 v166, 0x8000, v166
	v_add_u32_e32 v144, v167, v165
	v_add_u32_e32 v148, v166, v165
	v_xor_b32_e32 v169, 0x20, v165
	v_add_u32_e32 v145, v167, v169
	v_add_u32_e32 v149, v166, v169
	v_xor_b32_e32 v169, 0x40, v165
	v_add_u32_e32 v146, v167, v169
	v_add_u32_e32 v150, v166, v169
	v_xor_b32_e32 v169, 0x60, v165
	v_add_u32_e32 v147, v167, v169
	v_add_u32_e32 v151, v166, v169
	v_add_u32_e32 v152, 0x18000, v144
	v_add_u32_e32 v157, 0x18000, v148
	v_add_u32_e32 v153, 0x18000, v145
	v_add_u32_e32 v158, 0x18000, v149
	v_add_u32_e32 v154, 0x18000, v146
	v_add_u32_e32 v159, 0x18000, v150
	v_add_u32_e32 v155, 0x18000, v147
	v_add_u32_e32 v160, 0x18000, v151
	v_lshlrev_b32_e32 v164, 4, v129
	s_nop 0
	v_readfirstlane_b32 s25, v164
	s_mov_b32 s65, 0
	s_waitcnt vmcnt(6)
	s_barrier
	ds_read_b128 v[164:167], v144
	ds_read_b128 v[168:171], v144 offset:4096
	ds_read_b128 v[172:175], v148
	ds_read_b128 v[176:179], v148 offset:4096
	s_mov_b32 s64, 0x65c2100
	s_add_u32 m0, s25, 0x18000
	v_lshl_add_u64 v[226:227], v[142:143], 0, s[64:65]
	global_load_lds_dwordx4 v[226:227], off
	s_add_u32 m0, s25, 0x1a000
	v_lshl_add_u64 v[228:229], v[140:141], 0, s[64:65]
	global_load_lds_dwordx4 v[228:229], off
	ds_read_b128 v[180:183], v145
	ds_read_b128 v[184:187], v145 offset:4096
	ds_read_b128 v[218:221], v149
	ds_read_b128 v[222:225], v149 offset:4096
	s_waitcnt lgkmcnt(4)
	v_mfma_f32_32x32x16_bf16 v[48:63], v[164:167], v[172:175], v[48:63]
	s_add_u32 m0, s25, 0x1c000
	v_lshl_add_u64 v[226:227], v[138:139], 0, s[64:65]
	global_load_lds_dwordx4 v[226:227], off
	v_mfma_f32_32x32x16_bf16 v[32:47], v[164:167], v[176:179], v[32:47]
	v_mfma_f32_32x32x16_bf16 v[16:31], v[168:171], v[172:175], v[16:31]
	s_add_u32 m0, s25, 0x1e000
	v_lshl_add_u64 v[228:229], v[136:137], 0, s[64:65]
	global_load_lds_dwordx4 v[228:229], off
	v_mfma_f32_32x32x16_bf16 v[0:15], v[168:171], v[176:179], v[0:15]
	ds_read_b128 v[164:167], v146
	ds_read_b128 v[168:171], v146 offset:4096
	ds_read_b128 v[172:175], v150
	ds_read_b128 v[176:179], v150 offset:4096
	s_waitcnt lgkmcnt(4)
	v_mfma_f32_32x32x16_bf16 v[48:63], v[180:183], v[218:221], v[48:63]
	s_mov_b32 s64, 0x2740100
	s_add_u32 m0, s25, 0x20000
	v_lshl_add_u64 v[226:227], v[134:135], 0, s[64:65]
	global_load_lds_dwordx4 v[226:227], off
	v_mfma_f32_32x32x16_bf16 v[32:47], v[180:183], v[222:225], v[32:47]
	v_mfma_f32_32x32x16_bf16 v[16:31], v[184:187], v[218:221], v[16:31]
	s_add_u32 m0, s25, 0x22000
	v_lshl_add_u64 v[228:229], v[132:133], 0, s[64:65]
	global_load_lds_dwordx4 v[228:229], off
	v_mfma_f32_32x32x16_bf16 v[0:15], v[184:187], v[222:225], v[0:15]
	ds_read_b128 v[180:183], v147
	ds_read_b128 v[184:187], v147 offset:4096
	ds_read_b128 v[218:221], v151
	ds_read_b128 v[222:225], v151 offset:4096
	s_waitcnt lgkmcnt(4)
	v_mfma_f32_32x32x16_bf16 v[48:63], v[164:167], v[172:175], v[48:63]
	v_mfma_f32_32x32x16_bf16 v[32:47], v[164:167], v[176:179], v[32:47]
	v_mfma_f32_32x32x16_bf16 v[16:31], v[168:171], v[172:175], v[16:31]
	v_mfma_f32_32x32x16_bf16 v[0:15], v[168:171], v[176:179], v[0:15]
	s_waitcnt vmcnt(6) lgkmcnt(0)
	s_barrier
	ds_read_b128 v[164:167], v144 offset:49152
	ds_read_b128 v[168:171], v144 offset:53248
	ds_read_b128 v[172:175], v148 offset:49152
	ds_read_b128 v[176:179], v148 offset:53248
	v_mfma_f32_32x32x16_bf16 v[48:63], v[180:183], v[218:221], v[48:63]
	s_mov_b32 s64, 0x65c2180
	s_mov_b32 m0, s25
	v_lshl_add_u64 v[226:227], v[142:143], 0, s[64:65]
	global_load_lds_dwordx4 v[226:227], off
	v_mfma_f32_32x32x16_bf16 v[32:47], v[180:183], v[222:225], v[32:47]
	v_mfma_f32_32x32x16_bf16 v[16:31], v[184:187], v[218:221], v[16:31]
	s_add_u32 m0, s25, 0x2000
	v_lshl_add_u64 v[228:229], v[140:141], 0, s[64:65]
	global_load_lds_dwordx4 v[228:229], off
	v_mfma_f32_32x32x16_bf16 v[0:15], v[184:187], v[222:225], v[0:15]
	ds_read_b128 v[180:183], v145 offset:49152
	ds_read_b128 v[184:187], v145 offset:53248
	ds_read_b128 v[218:221], v149 offset:49152
	ds_read_b128 v[222:225], v149 offset:53248
	s_waitcnt lgkmcnt(4)
	v_mfma_f32_32x32x16_bf16 v[48:63], v[164:167], v[172:175], v[48:63]
	s_add_u32 m0, s25, 0x4000
	v_lshl_add_u64 v[226:227], v[138:139], 0, s[64:65]
	global_load_lds_dwordx4 v[226:227], off
	v_mfma_f32_32x32x16_bf16 v[32:47], v[164:167], v[176:179], v[32:47]
	v_mfma_f32_32x32x16_bf16 v[16:31], v[168:171], v[172:175], v[16:31]
	s_add_u32 m0, s25, 0x6000
	v_lshl_add_u64 v[228:229], v[136:137], 0, s[64:65]
	global_load_lds_dwordx4 v[228:229], off
	v_mfma_f32_32x32x16_bf16 v[0:15], v[168:171], v[176:179], v[0:15]
	ds_read_b128 v[164:167], v146 offset:49152
	ds_read_b128 v[168:171], v146 offset:53248
	ds_read_b128 v[172:175], v150 offset:49152
	ds_read_b128 v[176:179], v150 offset:53248
	s_waitcnt lgkmcnt(4)
	v_mfma_f32_32x32x16_bf16 v[48:63], v[180:183], v[218:221], v[48:63]
	s_mov_b32 s64, 0x2740180
	s_add_u32 m0, s25, 0x8000
	v_lshl_add_u64 v[226:227], v[134:135], 0, s[64:65]
	global_load_lds_dwordx4 v[226:227], off
	v_mfma_f32_32x32x16_bf16 v[32:47], v[180:183], v[222:225], v[32:47]
	v_mfma_f32_32x32x16_bf16 v[16:31], v[184:187], v[218:221], v[16:31]
	s_add_u32 m0, s25, 0xa000
	v_lshl_add_u64 v[228:229], v[132:133], 0, s[64:65]
	global_load_lds_dwordx4 v[228:229], off
	v_mfma_f32_32x32x16_bf16 v[0:15], v[184:187], v[222:225], v[0:15]
	ds_read_b128 v[180:183], v147 offset:49152
	ds_read_b128 v[184:187], v147 offset:53248
	ds_read_b128 v[218:221], v151 offset:49152
	ds_read_b128 v[222:225], v151 offset:53248
	s_waitcnt lgkmcnt(4)
	v_mfma_f32_32x32x16_bf16 v[48:63], v[164:167], v[172:175], v[48:63]
	v_mfma_f32_32x32x16_bf16 v[32:47], v[164:167], v[176:179], v[32:47]
	v_mfma_f32_32x32x16_bf16 v[16:31], v[168:171], v[172:175], v[16:31]
	v_mfma_f32_32x32x16_bf16 v[0:15], v[168:171], v[176:179], v[0:15]
	s_waitcnt vmcnt(6) lgkmcnt(0)
	s_barrier
;     ...
;   for (int kt = 0; kt < nk; ++kt) {
;     if (kt + 1 < nk) asm volatile("s_waitcnt vmcnt(6)" ::: "memory");
;     else asm volatile("s_waitcnt vmcnt(0)" ::: "memory");
;     __builtin_amdgcn_s_barrier();
;     asm volatile("" ::: "memory");
;     if (kt + 2 < nk) { const int st2 = (st >= 1) ? st - 1 : 2; GEMM_ISSUE(kt + 2, st2); }
;     const char* la = lds + st * STAGE_B;
;     const char* lb = la + 32768;
;     const unsigned sa_u = (unsigned)(size_t)la + arow_u, sb_u = (unsigned)(size_t)lb + brow_u;
;     const unsigned a0 = sa_u + co0, a1 = sa_u + co1, a2 = sa_u + co2, a3 = sa_u + co3;
;     const unsigned b0 = sb_u + co0, b1 = sb_u + co1, b2 = sb_u + co2, b3 = sb_u + co3;
;     {
;       bf16x8 p0, p1, q0, q1, u0, u1, w0, w1;
;       asm volatile(
;         "ds_read_b128 %4, %12\n\tds_read_b128 %5, %12 offset:4096\n\tds_read_b128 %6, %16\n\tds_read_b128 %7, %16 offset:4096\n\t"
;         "ds_read_b128 %8, %13\n\tds_read_b128 %9, %13 offset:4096\n\tds_read_b128 %10, %17\n\tds_read_b128 %11, %17 offset:4096\n\t"
;         "s_waitcnt lgkmcnt(4)\n\t"
;         "v_mfma_f32_32x32x16_bf16 %0, %4, %6, %0\n\tv_mfma_f32_32x32x16_bf16 %1, %4, %7, %1\n\tv_mfma_f32_32x32x16_bf16 %2, %5, %6, %2\n\tv_mfma_f32_32x32x16_bf16 %3, %5, %7, %3\n\t"
;         "ds_read_b128 %4, %14\n\tds_read_b128 %5, %14 offset:4096\n\tds_read_b128 %6, %18\n\tds_read_b128 %7, %18 offset:4096\n\t"
;         "s_waitcnt lgkmcnt(4)\n\t"
;         "v_mfma_f32_32x32x16_bf16 %0, %8, %10, %0\n\tv_mfma_f32_32x32x16_bf16 %1, %8, %11, %1\n\tv_mfma_f32_32x32x16_bf16 %2, %9, %10, %2\n\tv_mfma_f32_32x32x16_bf16 %3, %9, %11, %3\n\t"
;         "ds_read_b128 %8, %15\n\tds_read_b128 %9, %15 offset:4096\n\tds_read_b128 %10, %19\n\tds_read_b128 %11, %19 offset:4096\n\t"
;         "s_waitcnt lgkmcnt(4)\n\t"
;         "v_mfma_f32_32x32x16_bf16 %0, %4, %6, %0\n\tv_mfma_f32_32x32x16_bf16 %1, %4, %7, %1\n\tv_mfma_f32_32x32x16_bf16 %2, %5, %6, %2\n\tv_mfma_f32_32x32x16_bf16 %3, %5, %7, %3\n\t"
;         "s_waitcnt lgkmcnt(0)\n\t"
;         "v_mfma_f32_32x32x16_bf16 %0, %8, %10, %0\n\tv_mfma_f32_32x32x16_bf16 %1, %8, %11, %1\n\tv_mfma_f32_32x32x16_bf16 %2, %9, %10, %2\n\tv_mfma_f32_32x32x16_bf16 %3, %9, %11, %3"
;         : "+v"(acc[0][0]), "+v"(acc[0][1]), "+v"(acc[1][0]), "+v"(acc[1][1]),
;           "=&v"(p0), "=&v"(p1), "=&v"(q0), "=&v"(q1), "=&v"(u0), "=&v"(u1), "=&v"(w0), "=&v"(w1)
	ds_read_b128 v[164:167], v152
	ds_read_b128 v[168:171], v152 offset:4096
	ds_read_b128 v[172:175], v157
	ds_read_b128 v[176:179], v157 offset:4096
	v_mfma_f32_32x32x16_bf16 v[48:63], v[180:183], v[218:221], v[48:63]
	s_mov_b32 s64, 0x65c2200
	s_add_u32 m0, s25, 0xc000
	v_lshl_add_u64 v[226:227], v[142:143], 0, s[64:65]
	global_load_lds_dwordx4 v[226:227], off
	v_mfma_f32_32x32x16_bf16 v[32:47], v[180:183], v[222:225], v[32:47]
	v_mfma_f32_32x32x16_bf16 v[16:31], v[184:187], v[218:221], v[16:31]
	s_add_u32 m0, s25, 0xe000
	v_lshl_add_u64 v[228:229], v[140:141], 0, s[64:65]
	global_load_lds_dwordx4 v[228:229], off
	v_mfma_f32_32x32x16_bf16 v[0:15], v[184:187], v[222:225], v[0:15]
	ds_read_b128 v[180:183], v153
	ds_read_b128 v[184:187], v153 offset:4096
	ds_read_b128 v[218:221], v158
	ds_read_b128 v[222:225], v158 offset:4096
	s_waitcnt lgkmcnt(4)
	v_mfma_f32_32x32x16_bf16 v[48:63], v[164:167], v[172:175], v[48:63]
	s_add_u32 m0, s25, 0x10000
	v_lshl_add_u64 v[226:227], v[138:139], 0, s[64:65]
	global_load_lds_dwordx4 v[226:227], off
	v_mfma_f32_32x32x16_bf16 v[32:47], v[164:167], v[176:179], v[32:47]
	v_mfma_f32_32x32x16_bf16 v[16:31], v[168:171], v[172:175], v[16:31]
	s_add_u32 m0, s25, 0x12000
	v_lshl_add_u64 v[228:229], v[136:137], 0, s[64:65]
	global_load_lds_dwordx4 v[228:229], off
	v_mfma_f32_32x32x16_bf16 v[0:15], v[168:171], v[176:179], v[0:15]
	ds_read_b128 v[164:167], v154
	ds_read_b128 v[168:171], v154 offset:4096
	ds_read_b128 v[172:175], v159
	ds_read_b128 v[176:179], v159 offset:4096
	s_waitcnt lgkmcnt(4)
	v_mfma_f32_32x32x16_bf16 v[48:63], v[180:183], v[218:221], v[48:63]
	s_mov_b32 s64, 0x2740200
	s_add_u32 m0, s25, 0x14000
	v_lshl_add_u64 v[226:227], v[134:135], 0, s[64:65]
	global_load_lds_dwordx4 v[226:227], off
	v_mfma_f32_32x32x16_bf16 v[32:47], v[180:183], v[222:225], v[32:47]
	v_mfma_f32_32x32x16_bf16 v[16:31], v[184:187], v[218:221], v[16:31]
	s_add_u32 m0, s25, 0x16000
	v_lshl_add_u64 v[228:229], v[132:133], 0, s[64:65]
	global_load_lds_dwordx4 v[228:229], off
	v_mfma_f32_32x32x16_bf16 v[0:15], v[184:187], v[222:225], v[0:15]
	ds_read_b128 v[180:183], v155
	ds_read_b128 v[184:187], v155 offset:4096
	ds_read_b128 v[218:221], v160
	ds_read_b128 v[222:225], v160 offset:4096
	s_waitcnt lgkmcnt(4)
	v_mfma_f32_32x32x16_bf16 v[48:63], v[164:167], v[172:175], v[48:63]
	v_mfma_f32_32x32x16_bf16 v[32:47], v[164:167], v[176:179], v[32:47]
	v_mfma_f32_32x32x16_bf16 v[16:31], v[168:171], v[172:175], v[16:31]
	v_mfma_f32_32x32x16_bf16 v[0:15], v[168:171], v[176:179], v[0:15]
	s_waitcnt vmcnt(6) lgkmcnt(0)
	s_barrier
	ds_read_b128 v[164:167], v144
	ds_read_b128 v[168:171], v144 offset:4096
	ds_read_b128 v[172:175], v148
	ds_read_b128 v[176:179], v148 offset:4096
	v_mfma_f32_32x32x16_bf16 v[48:63], v[180:183], v[218:221], v[48:63]
	s_mov_b32 s64, 0x65c2280
	s_add_u32 m0, s25, 0x18000
	v_lshl_add_u64 v[226:227], v[142:143], 0, s[64:65]
	global_load_lds_dwordx4 v[226:227], off
	v_mfma_f32_32x32x16_bf16 v[32:47], v[180:183], v[222:225], v[32:47]
	v_mfma_f32_32x32x16_bf16 v[16:31], v[184:187], v[218:221], v[16:31]
	s_add_u32 m0, s25, 0x1a000
	v_lshl_add_u64 v[228:229], v[140:141], 0, s[64:65]
	global_load_lds_dwordx4 v[228:229], off
	v_mfma_f32_32x32x16_bf16 v[0:15], v[184:187], v[222:225], v[0:15]
	ds_read_b128 v[180:183], v145
	ds_read_b128 v[184:187], v145 offset:4096
	ds_read_b128 v[218:221], v149
	ds_read_b128 v[222:225], v149 offset:4096
	s_waitcnt lgkmcnt(4)
	v_mfma_f32_32x32x16_bf16 v[48:63], v[164:167], v[172:175], v[48:63]
	s_add_u32 m0, s25, 0x1c000
	v_lshl_add_u64 v[226:227], v[138:139], 0, s[64:65]
	global_load_lds_dwordx4 v[226:227], off
	v_mfma_f32_32x32x16_bf16 v[32:47], v[164:167], v[176:179], v[32:47]
	v_mfma_f32_32x32x16_bf16 v[16:31], v[168:171], v[172:175], v[16:31]
	s_add_u32 m0, s25, 0x1e000
	v_lshl_add_u64 v[228:229], v[136:137], 0, s[64:65]
	global_load_lds_dwordx4 v[228:229], off
	v_mfma_f32_32x32x16_bf16 v[0:15], v[168:171], v[176:179], v[0:15]
	ds_read_b128 v[164:167], v146
	ds_read_b128 v[168:171], v146 offset:4096
	ds_read_b128 v[172:175], v150
	ds_read_b128 v[176:179], v150 offset:4096
	s_waitcnt lgkmcnt(4)
	v_mfma_f32_32x32x16_bf16 v[48:63], v[180:183], v[218:221], v[48:63]
	s_mov_b32 s64, 0x2740280
	s_add_u32 m0, s25, 0x20000
	v_lshl_add_u64 v[226:227], v[134:135], 0, s[64:65]
	global_load_lds_dwordx4 v[226:227], off
	v_mfma_f32_32x32x16_bf16 v[32:47], v[180:183], v[222:225], v[32:47]
	v_mfma_f32_32x32x16_bf16 v[16:31], v[184:187], v[218:221], v[16:31]
	s_add_u32 m0, s25, 0x22000
	v_lshl_add_u64 v[228:229], v[132:133], 0, s[64:65]
	global_load_lds_dwordx4 v[228:229], off
	v_mfma_f32_32x32x16_bf16 v[0:15], v[184:187], v[222:225], v[0:15]
	ds_read_b128 v[180:183], v147
	ds_read_b128 v[184:187], v147 offset:4096
	ds_read_b128 v[218:221], v151
	ds_read_b128 v[222:225], v151 offset:4096
	s_waitcnt lgkmcnt(4)
	v_mfma_f32_32x32x16_bf16 v[48:63], v[164:167], v[172:175], v[48:63]
	v_mfma_f32_32x32x16_bf16 v[32:47], v[164:167], v[176:179], v[32:47]
	v_mfma_f32_32x32x16_bf16 v[16:31], v[168:171], v[172:175], v[16:31]
	v_mfma_f32_32x32x16_bf16 v[0:15], v[168:171], v[176:179], v[0:15]
	s_waitcnt vmcnt(6) lgkmcnt(0)
	s_barrier
;     ...
;   for (int kt = 0; kt < nk; ++kt) {
;     if (kt + 1 < nk) asm volatile("s_waitcnt vmcnt(6)" ::: "memory");
;     else asm volatile("s_waitcnt vmcnt(0)" ::: "memory");
;     __builtin_amdgcn_s_barrier();
;     asm volatile("" ::: "memory");
;     if (kt + 2 < nk) { const int st2 = (st >= 1) ? st - 1 : 2; GEMM_ISSUE(kt + 2, st2); }
;     const char* la = lds + st * STAGE_B;
;     const char* lb = la + 32768;
;     const unsigned sa_u = (unsigned)(size_t)la + arow_u, sb_u = (unsigned)(size_t)lb + brow_u;
;     const unsigned a0 = sa_u + co0, a1 = sa_u + co1, a2 = sa_u + co2, a3 = sa_u + co3;
;     const unsigned b0 = sb_u + co0, b1 = sb_u + co1, b2 = sb_u + co2, b3 = sb_u + co3;
;     {
;       bf16x8 p0, p1, q0, q1, u0, u1, w0, w1;
;       asm volatile(
;         "ds_read_b128 %4, %12\n\tds_read_b128 %5, %12 offset:4096\n\tds_read_b128 %6, %16\n\tds_read_b128 %7, %16 offset:4096\n\t"
;         "ds_read_b128 %8, %13\n\tds_read_b128 %9, %13 offset:4096\n\tds_read_b128 %10, %17\n\tds_read_b128 %11, %17 offset:4096\n\t"
;         "s_waitcnt lgkmcnt(4)\n\t"
;         "v_mfma_f32_32x32x16_bf16 %0, %4, %6, %0\n\tv_mfma_f32_32x32x16_bf16 %1, %4, %7, %1\n\tv_mfma_f32_32x32x16_bf16 %2, %5, %6, %2\n\tv_mfma_f32_32x32x16_bf16 %3, %5, %7, %3\n\t"
;         "ds_read_b128 %4, %14\n\tds_read_b128 %5, %14 offset:4096\n\tds_read_b128 %6, %18\n\tds_read_b128 %7, %18 offset:4096\n\t"
;         "s_waitcnt lgkmcnt(4)\n\t"
;         "v_mfma_f32_32x32x16_bf16 %0, %8, %10, %0\n\tv_mfma_f32_32x32x16_bf16 %1, %8, %11, %1\n\tv_mfma_f32_32x32x16_bf16 %2, %9, %10, %2\n\tv_mfma_f32_32x32x16_bf16 %3, %9, %11, %3\n\t"
;         "ds_read_b128 %8, %15\n\tds_read_b128 %9, %15 offset:4096\n\tds_read_b128 %10, %19\n\tds_read_b128 %11, %19 offset:4096\n\t"
;         "s_waitcnt lgkmcnt(4)\n\t"
;         "v_mfma_f32_32x32x16_bf16 %0, %4, %6, %0\n\tv_mfma_f32_32x32x16_bf16 %1, %4, %7, %1\n\tv_mfma_f32_32x32x16_bf16 %2, %5, %6, %2\n\tv_mfma_f32_32x32x16_bf16 %3, %5, %7, %3\n\t"
;         "s_waitcnt lgkmcnt(0)\n\t"
;         "v_mfma_f32_32x32x16_bf16 %0, %8, %10, %0\n\tv_mfma_f32_32x32x16_bf16 %1, %8, %11, %1\n\tv_mfma_f32_32x32x16_bf16 %2, %9, %10, %2\n\tv_mfma_f32_32x32x16_bf16 %3, %9, %11, %3"
;         : "+v"(acc[0][0]), "+v"(acc[0][1]), "+v"(acc[1][0]), "+v"(acc[1][1]),
;           "=&v"(p0), "=&v"(p1), "=&v"(q0), "=&v"(q1), "=&v"(u0), "=&v"(u1), "=&v"(w0), "=&v"(w1)
	ds_read_b128 v[164:167], v144 offset:49152
	ds_read_b128 v[168:171], v144 offset:53248
	ds_read_b128 v[172:175], v148 offset:49152
	ds_read_b128 v[176:179], v148 offset:53248
	v_mfma_f32_32x32x16_bf16 v[48:63], v[180:183], v[218:221], v[48:63]
	s_mov_b32 s64, 0x65c2300
	s_mov_b32 m0, s25
	v_lshl_add_u64 v[226:227], v[142:143], 0, s[64:65]
	global_load_lds_dwordx4 v[226:227], off
	v_mfma_f32_32x32x16_bf16 v[32:47], v[180:183], v[222:225], v[32:47]
	v_mfma_f32_32x32x16_bf16 v[16:31], v[184:187], v[218:221], v[16:31]
	s_add_u32 m0, s25, 0x2000
	v_lshl_add_u64 v[228:229], v[140:141], 0, s[64:65]
	global_load_lds_dwordx4 v[228:229], off
	v_mfma_f32_32x32x16_bf16 v[0:15], v[184:187], v[222:225], v[0:15]
	ds_read_b128 v[180:183], v145 offset:49152
	ds_read_b128 v[184:187], v145 offset:53248
	ds_read_b128 v[218:221], v149 offset:49152
	ds_read_b128 v[222:225], v149 offset:53248
	s_waitcnt lgkmcnt(4)
	v_mfma_f32_32x32x16_bf16 v[48:63], v[164:167], v[172:175], v[48:63]
	s_add_u32 m0, s25, 0x4000
	v_lshl_add_u64 v[226:227], v[138:139], 0, s[64:65]
	global_load_lds_dwordx4 v[226:227], off
	v_mfma_f32_32x32x16_bf16 v[32:47], v[164:167], v[176:179], v[32:47]
	v_mfma_f32_32x32x16_bf16 v[16:31], v[168:171], v[172:175], v[16:31]
	s_add_u32 m0, s25, 0x6000
	v_lshl_add_u64 v[228:229], v[136:137], 0, s[64:65]
	global_load_lds_dwordx4 v[228:229], off
	v_mfma_f32_32x32x16_bf16 v[0:15], v[168:171], v[176:179], v[0:15]
	ds_read_b128 v[164:167], v146 offset:49152
	ds_read_b128 v[168:171], v146 offset:53248
	ds_read_b128 v[172:175], v150 offset:49152
	ds_read_b128 v[176:179], v150 offset:53248
	s_waitcnt lgkmcnt(4)
	v_mfma_f32_32x32x16_bf16 v[48:63], v[180:183], v[218:221], v[48:63]
	s_mov_b32 s64, 0x2740300
	s_add_u32 m0, s25, 0x8000
	v_lshl_add_u64 v[226:227], v[134:135], 0, s[64:65]
	global_load_lds_dwordx4 v[226:227], off
	v_mfma_f32_32x32x16_bf16 v[32:47], v[180:183], v[222:225], v[32:47]
	v_mfma_f32_32x32x16_bf16 v[16:31], v[184:187], v[218:221], v[16:31]
	s_add_u32 m0, s25, 0xa000
	v_lshl_add_u64 v[228:229], v[132:133], 0, s[64:65]
	global_load_lds_dwordx4 v[228:229], off
	v_mfma_f32_32x32x16_bf16 v[0:15], v[184:187], v[222:225], v[0:15]
	ds_read_b128 v[180:183], v147 offset:49152
	ds_read_b128 v[184:187], v147 offset:53248
	ds_read_b128 v[218:221], v151 offset:49152
	ds_read_b128 v[222:225], v151 offset:53248
	s_waitcnt lgkmcnt(4)
	v_mfma_f32_32x32x16_bf16 v[48:63], v[164:167], v[172:175], v[48:63]
	v_mfma_f32_32x32x16_bf16 v[32:47], v[164:167], v[176:179], v[32:47]
	v_mfma_f32_32x32x16_bf16 v[16:31], v[168:171], v[172:175], v[16:31]
	v_mfma_f32_32x32x16_bf16 v[0:15], v[168:171], v[176:179], v[0:15]
	s_waitcnt vmcnt(6) lgkmcnt(0)
	s_barrier
	ds_read_b128 v[164:167], v152
	ds_read_b128 v[168:171], v152 offset:4096
	ds_read_b128 v[172:175], v157
	ds_read_b128 v[176:179], v157 offset:4096
	v_mfma_f32_32x32x16_bf16 v[48:63], v[180:183], v[218:221], v[48:63]
	s_mov_b32 s64, 0x65c2380
	s_add_u32 m0, s25, 0xc000
	v_lshl_add_u64 v[226:227], v[142:143], 0, s[64:65]
	global_load_lds_dwordx4 v[226:227], off
	v_mfma_f32_32x32x16_bf16 v[32:47], v[180:183], v[222:225], v[32:47]
	v_mfma_f32_32x32x16_bf16 v[16:31], v[184:187], v[218:221], v[16:31]
	s_add_u32 m0, s25, 0xe000
	v_lshl_add_u64 v[228:229], v[140:141], 0, s[64:65]
	global_load_lds_dwordx4 v[228:229], off
	v_mfma_f32_32x32x16_bf16 v[0:15], v[184:187], v[222:225], v[0:15]
	ds_read_b128 v[180:183], v153
	ds_read_b128 v[184:187], v153 offset:4096
	ds_read_b128 v[218:221], v158
	ds_read_b128 v[222:225], v158 offset:4096
	s_waitcnt lgkmcnt(4)
	v_mfma_f32_32x32x16_bf16 v[48:63], v[164:167], v[172:175], v[48:63]
	s_add_u32 m0, s25, 0x10000
	v_lshl_add_u64 v[226:227], v[138:139], 0, s[64:65]
	global_load_lds_dwordx4 v[226:227], off
	v_mfma_f32_32x32x16_bf16 v[32:47], v[164:167], v[176:179], v[32:47]
	v_mfma_f32_32x32x16_bf16 v[16:31], v[168:171], v[172:175], v[16:31]
	s_add_u32 m0, s25, 0x12000
	v_lshl_add_u64 v[228:229], v[136:137], 0, s[64:65]
	global_load_lds_dwordx4 v[228:229], off
	v_mfma_f32_32x32x16_bf16 v[0:15], v[168:171], v[176:179], v[0:15]
	ds_read_b128 v[164:167], v154
	ds_read_b128 v[168:171], v154 offset:4096
	ds_read_b128 v[172:175], v159
	ds_read_b128 v[176:179], v159 offset:4096
	s_waitcnt lgkmcnt(4)
	v_mfma_f32_32x32x16_bf16 v[48:63], v[180:183], v[218:221], v[48:63]
	s_mov_b32 s64, 0x2740380
	s_add_u32 m0, s25, 0x14000
	v_lshl_add_u64 v[226:227], v[134:135], 0, s[64:65]
	global_load_lds_dwordx4 v[226:227], off
	v_mfma_f32_32x32x16_bf16 v[32:47], v[180:183], v[222:225], v[32:47]
	v_mfma_f32_32x32x16_bf16 v[16:31], v[184:187], v[218:221], v[16:31]
	s_add_u32 m0, s25, 0x16000
	v_lshl_add_u64 v[228:229], v[132:133], 0, s[64:65]
	global_load_lds_dwordx4 v[228:229], off
	v_mfma_f32_32x32x16_bf16 v[0:15], v[184:187], v[222:225], v[0:15]
	ds_read_b128 v[180:183], v155
	ds_read_b128 v[184:187], v155 offset:4096
	ds_read_b128 v[218:221], v160
	ds_read_b128 v[222:225], v160 offset:4096
	s_waitcnt lgkmcnt(4)
	v_mfma_f32_32x32x16_bf16 v[48:63], v[164:167], v[172:175], v[48:63]
	v_mfma_f32_32x32x16_bf16 v[32:47], v[164:167], v[176:179], v[32:47]
	v_mfma_f32_32x32x16_bf16 v[16:31], v[168:171], v[172:175], v[16:31]
	v_mfma_f32_32x32x16_bf16 v[0:15], v[168:171], v[176:179], v[0:15]
	s_waitcnt vmcnt(6) lgkmcnt(0)
	s_barrier
;     ...
;   for (int kt = 0; kt < nk; ++kt) {
;     if (kt + 1 < nk) asm volatile("s_waitcnt vmcnt(6)" ::: "memory");
;     else asm volatile("s_waitcnt vmcnt(0)" ::: "memory");
;     __builtin_amdgcn_s_barrier();
;     asm volatile("" ::: "memory");
;     if (kt + 2 < nk) { const int st2 = (st >= 1) ? st - 1 : 2; GEMM_ISSUE(kt + 2, st2); }
;     const char* la = lds + st * STAGE_B;
;     const char* lb = la + 32768;
;     const unsigned sa_u = (unsigned)(size_t)la + arow_u, sb_u = (unsigned)(size_t)lb + brow_u;
;     const unsigned a0 = sa_u + co0, a1 = sa_u + co1, a2 = sa_u + co2, a3 = sa_u + co3;
;     const unsigned b0 = sb_u + co0, b1 = sb_u + co1, b2 = sb_u + co2, b3 = sb_u + co3;
;     {
;       bf16x8 p0, p1, q0, q1, u0, u1, w0, w1;
;       asm volatile(
;         "ds_read_b128 %4, %12\n\tds_read_b128 %5, %12 offset:4096\n\tds_read_b128 %6, %16\n\tds_read_b128 %7, %16 offset:4096\n\t"
;         "ds_read_b128 %8, %13\n\tds_read_b128 %9, %13 offset:4096\n\tds_read_b128 %10, %17\n\tds_read_b128 %11, %17 offset:4096\n\t"
;         "s_waitcnt lgkmcnt(4)\n\t"
;         "v_mfma_f32_32x32x16_bf16 %0, %4, %6, %0\n\tv_mfma_f32_32x32x16_bf16 %1, %4, %7, %1\n\tv_mfma_f32_32x32x16_bf16 %2, %5, %6, %2\n\tv_mfma_f32_32x32x16_bf16 %3, %5, %7, %3\n\t"
;         "ds_read_b128 %4, %14\n\tds_read_b128 %5, %14 offset:4096\n\tds_read_b128 %6, %18\n\tds_read_b128 %7, %18 offset:4096\n\t"
;         "s_waitcnt lgkmcnt(4)\n\t"
;         "v_mfma_f32_32x32x16_bf16 %0, %8, %10, %0\n\tv_mfma_f32_32x32x16_bf16 %1, %8, %11, %1\n\tv_mfma_f32_32x32x16_bf16 %2, %9, %10, %2\n\tv_mfma_f32_32x32x16_bf16 %3, %9, %11, %3\n\t"
;         "ds_read_b128 %8, %15\n\tds_read_b128 %9, %15 offset:4096\n\tds_read_b128 %10, %19\n\tds_read_b128 %11, %19 offset:4096\n\t"
;         "s_waitcnt lgkmcnt(4)\n\t"
;         "v_mfma_f32_32x32x16_bf16 %0, %4, %6, %0\n\tv_mfma_f32_32x32x16_bf16 %1, %4, %7, %1\n\tv_mfma_f32_32x32x16_bf16 %2, %5, %6, %2\n\tv_mfma_f32_32x32x16_bf16 %3, %5, %7, %3\n\t"
;         "s_waitcnt lgkmcnt(0)\n\t"
;         "v_mfma_f32_32x32x16_bf16 %0, %8, %10, %0\n\tv_mfma_f32_32x32x16_bf16 %1, %8, %11, %1\n\tv_mfma_f32_32x32x16_bf16 %2, %9, %10, %2\n\tv_mfma_f32_32x32x16_bf16 %3, %9, %11, %3"
;         : "+v"(acc[0][0]), "+v"(acc[0][1]), "+v"(acc[1][0]), "+v"(acc[1][1]),
;           "=&v"(p0), "=&v"(p1), "=&v"(q0), "=&v"(q1), "=&v"(u0), "=&v"(u1), "=&v"(w0), "=&v"(w1)
	ds_read_b128 v[164:167], v144
	ds_read_b128 v[168:171], v144 offset:4096
	ds_read_b128 v[172:175], v148
	ds_read_b128 v[176:179], v148 offset:4096
	v_mfma_f32_32x32x16_bf16 v[48:63], v[180:183], v[218:221], v[48:63]
	s_mov_b32 s64, 0x65c2400
	s_add_u32 m0, s25, 0x18000
	v_lshl_add_u64 v[226:227], v[142:143], 0, s[64:65]
	global_load_lds_dwordx4 v[226:227], off
	v_mfma_f32_32x32x16_bf16 v[32:47], v[180:183], v[222:225], v[32:47]
	v_mfma_f32_32x32x16_bf16 v[16:31], v[184:187], v[218:221], v[16:31]
	s_add_u32 m0, s25, 0x1a000
	v_lshl_add_u64 v[228:229], v[140:141], 0, s[64:65]
	global_load_lds_dwordx4 v[228:229], off
	v_mfma_f32_32x32x16_bf16 v[0:15], v[184:187], v[222:225], v[0:15]
	ds_read_b128 v[180:183], v145
	ds_read_b128 v[184:187], v145 offset:4096
	ds_read_b128 v[218:221], v149
	ds_read_b128 v[222:225], v149 offset:4096
	s_waitcnt lgkmcnt(4)
	v_mfma_f32_32x32x16_bf16 v[48:63], v[164:167], v[172:175], v[48:63]
	s_add_u32 m0, s25, 0x1c000
	v_lshl_add_u64 v[226:227], v[138:139], 0, s[64:65]
	global_load_lds_dwordx4 v[226:227], off
	v_mfma_f32_32x32x16_bf16 v[32:47], v[164:167], v[176:179], v[32:47]
	v_mfma_f32_32x32x16_bf16 v[16:31], v[168:171], v[172:175], v[16:31]
	s_add_u32 m0, s25, 0x1e000
	v_lshl_add_u64 v[228:229], v[136:137], 0, s[64:65]
	global_load_lds_dwordx4 v[228:229], off
	v_mfma_f32_32x32x16_bf16 v[0:15], v[168:171], v[176:179], v[0:15]
	ds_read_b128 v[164:167], v146
	ds_read_b128 v[168:171], v146 offset:4096
	ds_read_b128 v[172:175], v150
	ds_read_b128 v[176:179], v150 offset:4096
	s_waitcnt lgkmcnt(4)
	v_mfma_f32_32x32x16_bf16 v[48:63], v[180:183], v[218:221], v[48:63]
	s_mov_b32 s64, 0x2740400
	s_add_u32 m0, s25, 0x20000
	v_lshl_add_u64 v[226:227], v[134:135], 0, s[64:65]
	global_load_lds_dwordx4 v[226:227], off
	v_mfma_f32_32x32x16_bf16 v[32:47], v[180:183], v[222:225], v[32:47]
	v_mfma_f32_32x32x16_bf16 v[16:31], v[184:187], v[218:221], v[16:31]
	s_add_u32 m0, s25, 0x22000
	v_lshl_add_u64 v[228:229], v[132:133], 0, s[64:65]
	global_load_lds_dwordx4 v[228:229], off
	v_mfma_f32_32x32x16_bf16 v[0:15], v[184:187], v[222:225], v[0:15]
	ds_read_b128 v[180:183], v147
	ds_read_b128 v[184:187], v147 offset:4096
	ds_read_b128 v[218:221], v151
	ds_read_b128 v[222:225], v151 offset:4096
	s_waitcnt lgkmcnt(4)
	v_mfma_f32_32x32x16_bf16 v[48:63], v[164:167], v[172:175], v[48:63]
	v_mfma_f32_32x32x16_bf16 v[32:47], v[164:167], v[176:179], v[32:47]
	v_mfma_f32_32x32x16_bf16 v[16:31], v[168:171], v[172:175], v[16:31]
	v_mfma_f32_32x32x16_bf16 v[0:15], v[168:171], v[176:179], v[0:15]
	s_waitcnt vmcnt(6) lgkmcnt(0)
	s_barrier
	ds_read_b128 v[164:167], v144 offset:49152
	ds_read_b128 v[168:171], v144 offset:53248
	ds_read_b128 v[172:175], v148 offset:49152
	ds_read_b128 v[176:179], v148 offset:53248
	v_mfma_f32_32x32x16_bf16 v[48:63], v[180:183], v[218:221], v[48:63]
	s_mov_b32 s64, 0x65c2480
	s_mov_b32 m0, s25
	v_lshl_add_u64 v[226:227], v[142:143], 0, s[64:65]
	global_load_lds_dwordx4 v[226:227], off
	v_mfma_f32_32x32x16_bf16 v[32:47], v[180:183], v[222:225], v[32:47]
	v_mfma_f32_32x32x16_bf16 v[16:31], v[184:187], v[218:221], v[16:31]
	s_add_u32 m0, s25, 0x2000
	v_lshl_add_u64 v[228:229], v[140:141], 0, s[64:65]
	global_load_lds_dwordx4 v[228:229], off
	v_mfma_f32_32x32x16_bf16 v[0:15], v[184:187], v[222:225], v[0:15]
	ds_read_b128 v[180:183], v145 offset:49152
	ds_read_b128 v[184:187], v145 offset:53248
	ds_read_b128 v[218:221], v149 offset:49152
	ds_read_b128 v[222:225], v149 offset:53248
	s_waitcnt lgkmcnt(4)
	v_mfma_f32_32x32x16_bf16 v[48:63], v[164:167], v[172:175], v[48:63]
	s_add_u32 m0, s25, 0x4000
	v_lshl_add_u64 v[226:227], v[138:139], 0, s[64:65]
	global_load_lds_dwordx4 v[226:227], off
	v_mfma_f32_32x32x16_bf16 v[32:47], v[164:167], v[176:179], v[32:47]
	v_mfma_f32_32x32x16_bf16 v[16:31], v[168:171], v[172:175], v[16:31]
	s_add_u32 m0, s25, 0x6000
	v_lshl_add_u64 v[228:229], v[136:137], 0, s[64:65]
	global_load_lds_dwordx4 v[228:229], off
	v_mfma_f32_32x32x16_bf16 v[0:15], v[168:171], v[176:179], v[0:15]
	ds_read_b128 v[164:167], v146 offset:49152
	ds_read_b128 v[168:171], v146 offset:53248
	ds_read_b128 v[172:175], v150 offset:49152
	ds_read_b128 v[176:179], v150 offset:53248
	s_waitcnt lgkmcnt(4)
	v_mfma_f32_32x32x16_bf16 v[48:63], v[180:183], v[218:221], v[48:63]
	s_mov_b32 s64, 0x2740480
	s_add_u32 m0, s25, 0x8000
	v_lshl_add_u64 v[226:227], v[134:135], 0, s[64:65]
	global_load_lds_dwordx4 v[226:227], off
	v_mfma_f32_32x32x16_bf16 v[32:47], v[180:183], v[222:225], v[32:47]
	v_mfma_f32_32x32x16_bf16 v[16:31], v[184:187], v[218:221], v[16:31]
	s_add_u32 m0, s25, 0xa000
	v_lshl_add_u64 v[228:229], v[132:133], 0, s[64:65]
	global_load_lds_dwordx4 v[228:229], off
	v_mfma_f32_32x32x16_bf16 v[0:15], v[184:187], v[222:225], v[0:15]
	ds_read_b128 v[180:183], v147 offset:49152
	ds_read_b128 v[184:187], v147 offset:53248
	ds_read_b128 v[218:221], v151 offset:49152
	ds_read_b128 v[222:225], v151 offset:53248
	s_waitcnt lgkmcnt(4)
	v_mfma_f32_32x32x16_bf16 v[48:63], v[164:167], v[172:175], v[48:63]
	v_mfma_f32_32x32x16_bf16 v[32:47], v[164:167], v[176:179], v[32:47]
	v_mfma_f32_32x32x16_bf16 v[16:31], v[168:171], v[172:175], v[16:31]
	v_mfma_f32_32x32x16_bf16 v[0:15], v[168:171], v[176:179], v[0:15]
	s_waitcnt vmcnt(6) lgkmcnt(0)
	s_barrier
;     ...
;   for (int kt = 0; kt < nk; ++kt) {
;     if (kt + 1 < nk) asm volatile("s_waitcnt vmcnt(6)" ::: "memory");
;     else asm volatile("s_waitcnt vmcnt(0)" ::: "memory");
;     __builtin_amdgcn_s_barrier();
;     asm volatile("" ::: "memory");
;     if (kt + 2 < nk) { const int st2 = (st >= 1) ? st - 1 : 2; GEMM_ISSUE(kt + 2, st2); }
;     const char* la = lds + st * STAGE_B;
;     const char* lb = la + 32768;
;     const unsigned sa_u = (unsigned)(size_t)la + arow_u, sb_u = (unsigned)(size_t)lb + brow_u;
;     const unsigned a0 = sa_u + co0, a1 = sa_u + co1, a2 = sa_u + co2, a3 = sa_u + co3;
;     const unsigned b0 = sb_u + co0, b1 = sb_u + co1, b2 = sb_u + co2, b3 = sb_u + co3;
;     {
;       bf16x8 p0, p1, q0, q1, u0, u1, w0, w1;
;       asm volatile(
;         "ds_read_b128 %4, %12\n\tds_read_b128 %5, %12 offset:4096\n\tds_read_b128 %6, %16\n\tds_read_b128 %7, %16 offset:4096\n\t"
;         "ds_read_b128 %8, %13\n\tds_read_b128 %9, %13 offset:4096\n\tds_read_b128 %10, %17\n\tds_read_b128 %11, %17 offset:4096\n\t"
;         "s_waitcnt lgkmcnt(4)\n\t"
;         "v_mfma_f32_32x32x16_bf16 %0, %4, %6, %0\n\tv_mfma_f32_32x32x16_bf16 %1, %4, %7, %1\n\tv_mfma_f32_32x32x16_bf16 %2, %5, %6, %2\n\tv_mfma_f32_32x32x16_bf16 %3, %5, %7, %3\n\t"
;         "ds_read_b128 %4, %14\n\tds_read_b128 %5, %14 offset:4096\n\tds_read_b128 %6, %18\n\tds_read_b128 %7, %18 offset:4096\n\t"
;         "s_waitcnt lgkmcnt(4)\n\t"
;         "v_mfma_f32_32x32x16_bf16 %0, %8, %10, %0\n\tv_mfma_f32_32x32x16_bf16 %1, %8, %11, %1\n\tv_mfma_f32_32x32x16_bf16 %2, %9, %10, %2\n\tv_mfma_f32_32x32x16_bf16 %3, %9, %11, %3\n\t"
;         "ds_read_b128 %8, %15\n\tds_read_b128 %9, %15 offset:4096\n\tds_read_b128 %10, %19\n\tds_read_b128 %11, %19 offset:4096\n\t"
;         "s_waitcnt lgkmcnt(4)\n\t"
;         "v_mfma_f32_32x32x16_bf16 %0, %4, %6, %0\n\tv_mfma_f32_32x32x16_bf16 %1, %4, %7, %1\n\tv_mfma_f32_32x32x16_bf16 %2, %5, %6, %2\n\tv_mfma_f32_32x32x16_bf16 %3, %5, %7, %3\n\t"
;         "s_waitcnt lgkmcnt(0)\n\t"
;         "v_mfma_f32_32x32x16_bf16 %0, %8, %10, %0\n\tv_mfma_f32_32x32x16_bf16 %1, %8, %11, %1\n\tv_mfma_f32_32x32x16_bf16 %2, %9, %10, %2\n\tv_mfma_f32_32x32x16_bf16 %3, %9, %11, %3"
;         : "+v"(acc[0][0]), "+v"(acc[0][1]), "+v"(acc[1][0]), "+v"(acc[1][1]),
;           "=&v"(p0), "=&v"(p1), "=&v"(q0), "=&v"(q1), "=&v"(u0), "=&v"(u1), "=&v"(w0), "=&v"(w1)
	ds_read_b128 v[164:167], v152
	ds_read_b128 v[168:171], v152 offset:4096
	ds_read_b128 v[172:175], v157
	ds_read_b128 v[176:179], v157 offset:4096
	v_mfma_f32_32x32x16_bf16 v[48:63], v[180:183], v[218:221], v[48:63]
	s_mov_b32 s64, 0x65c2500
	s_add_u32 m0, s25, 0xc000
	v_lshl_add_u64 v[226:227], v[142:143], 0, s[64:65]
	global_load_lds_dwordx4 v[226:227], off
	v_mfma_f32_32x32x16_bf16 v[32:47], v[180:183], v[222:225], v[32:47]
	v_mfma_f32_32x32x16_bf16 v[16:31], v[184:187], v[218:221], v[16:31]
	s_add_u32 m0, s25, 0xe000
	v_lshl_add_u64 v[228:229], v[140:141], 0, s[64:65]
	global_load_lds_dwordx4 v[228:229], off
	v_mfma_f32_32x32x16_bf16 v[0:15], v[184:187], v[222:225], v[0:15]
	ds_read_b128 v[180:183], v153
	ds_read_b128 v[184:187], v153 offset:4096
	ds_read_b128 v[218:221], v158
	ds_read_b128 v[222:225], v158 offset:4096
	s_waitcnt lgkmcnt(4)
	v_mfma_f32_32x32x16_bf16 v[48:63], v[164:167], v[172:175], v[48:63]
	s_add_u32 m0, s25, 0x10000
	v_lshl_add_u64 v[226:227], v[138:139], 0, s[64:65]
	global_load_lds_dwordx4 v[226:227], off
	v_mfma_f32_32x32x16_bf16 v[32:47], v[164:167], v[176:179], v[32:47]
	v_mfma_f32_32x32x16_bf16 v[16:31], v[168:171], v[172:175], v[16:31]
	s_add_u32 m0, s25, 0x12000
	v_lshl_add_u64 v[228:229], v[136:137], 0, s[64:65]
	global_load_lds_dwordx4 v[228:229], off
	v_mfma_f32_32x32x16_bf16 v[0:15], v[168:171], v[176:179], v[0:15]
	ds_read_b128 v[164:167], v154
	ds_read_b128 v[168:171], v154 offset:4096
	ds_read_b128 v[172:175], v159
	ds_read_b128 v[176:179], v159 offset:4096
	s_waitcnt lgkmcnt(4)
	v_mfma_f32_32x32x16_bf16 v[48:63], v[180:183], v[218:221], v[48:63]
	s_mov_b32 s64, 0x2740500
	s_add_u32 m0, s25, 0x14000
	v_lshl_add_u64 v[226:227], v[134:135], 0, s[64:65]
	global_load_lds_dwordx4 v[226:227], off
	v_mfma_f32_32x32x16_bf16 v[32:47], v[180:183], v[222:225], v[32:47]
	v_mfma_f32_32x32x16_bf16 v[16:31], v[184:187], v[218:221], v[16:31]
	s_add_u32 m0, s25, 0x16000
	v_lshl_add_u64 v[228:229], v[132:133], 0, s[64:65]
	global_load_lds_dwordx4 v[228:229], off
	v_mfma_f32_32x32x16_bf16 v[0:15], v[184:187], v[222:225], v[0:15]
	ds_read_b128 v[180:183], v155
	ds_read_b128 v[184:187], v155 offset:4096
	ds_read_b128 v[218:221], v160
	ds_read_b128 v[222:225], v160 offset:4096
	s_waitcnt lgkmcnt(4)
	v_mfma_f32_32x32x16_bf16 v[48:63], v[164:167], v[172:175], v[48:63]
	v_mfma_f32_32x32x16_bf16 v[32:47], v[164:167], v[176:179], v[32:47]
	v_mfma_f32_32x32x16_bf16 v[16:31], v[168:171], v[172:175], v[16:31]
	v_mfma_f32_32x32x16_bf16 v[0:15], v[168:171], v[176:179], v[0:15]
	s_waitcnt vmcnt(6) lgkmcnt(0)
	s_barrier
	ds_read_b128 v[164:167], v144
	ds_read_b128 v[168:171], v144 offset:4096
	ds_read_b128 v[172:175], v148
	ds_read_b128 v[176:179], v148 offset:4096
	v_mfma_f32_32x32x16_bf16 v[48:63], v[180:183], v[218:221], v[48:63]
	s_mov_b32 s64, 0x65c2580
	s_add_u32 m0, s25, 0x18000
	v_lshl_add_u64 v[226:227], v[142:143], 0, s[64:65]
	global_load_lds_dwordx4 v[226:227], off
	v_mfma_f32_32x32x16_bf16 v[32:47], v[180:183], v[222:225], v[32:47]
	v_mfma_f32_32x32x16_bf16 v[16:31], v[184:187], v[218:221], v[16:31]
	s_add_u32 m0, s25, 0x1a000
	v_lshl_add_u64 v[228:229], v[140:141], 0, s[64:65]
	global_load_lds_dwordx4 v[228:229], off
	v_mfma_f32_32x32x16_bf16 v[0:15], v[184:187], v[222:225], v[0:15]
	ds_read_b128 v[180:183], v145
	ds_read_b128 v[184:187], v145 offset:4096
	ds_read_b128 v[218:221], v149
	ds_read_b128 v[222:225], v149 offset:4096
	s_waitcnt lgkmcnt(4)
	v_mfma_f32_32x32x16_bf16 v[48:63], v[164:167], v[172:175], v[48:63]
	s_add_u32 m0, s25, 0x1c000
	v_lshl_add_u64 v[226:227], v[138:139], 0, s[64:65]
	global_load_lds_dwordx4 v[226:227], off
	v_mfma_f32_32x32x16_bf16 v[32:47], v[164:167], v[176:179], v[32:47]
	v_mfma_f32_32x32x16_bf16 v[16:31], v[168:171], v[172:175], v[16:31]
	s_add_u32 m0, s25, 0x1e000
	v_lshl_add_u64 v[228:229], v[136:137], 0, s[64:65]
	global_load_lds_dwordx4 v[228:229], off
	v_mfma_f32_32x32x16_bf16 v[0:15], v[168:171], v[176:179], v[0:15]
	ds_read_b128 v[164:167], v146
	ds_read_b128 v[168:171], v146 offset:4096
	ds_read_b128 v[172:175], v150
	ds_read_b128 v[176:179], v150 offset:4096
	s_waitcnt lgkmcnt(4)
	v_mfma_f32_32x32x16_bf16 v[48:63], v[180:183], v[218:221], v[48:63]
	s_mov_b32 s64, 0x2740580
	s_add_u32 m0, s25, 0x20000
	v_lshl_add_u64 v[226:227], v[134:135], 0, s[64:65]
	global_load_lds_dwordx4 v[226:227], off
	v_mfma_f32_32x32x16_bf16 v[32:47], v[180:183], v[222:225], v[32:47]
	v_mfma_f32_32x32x16_bf16 v[16:31], v[184:187], v[218:221], v[16:31]
	s_add_u32 m0, s25, 0x22000
	v_lshl_add_u64 v[228:229], v[132:133], 0, s[64:65]
	global_load_lds_dwordx4 v[228:229], off
	v_mfma_f32_32x32x16_bf16 v[0:15], v[184:187], v[222:225], v[0:15]
	ds_read_b128 v[180:183], v147
	ds_read_b128 v[184:187], v147 offset:4096
	ds_read_b128 v[218:221], v151
	ds_read_b128 v[222:225], v151 offset:4096
	s_waitcnt lgkmcnt(4)
	v_mfma_f32_32x32x16_bf16 v[48:63], v[164:167], v[172:175], v[48:63]
	v_mfma_f32_32x32x16_bf16 v[32:47], v[164:167], v[176:179], v[32:47]
	v_mfma_f32_32x32x16_bf16 v[16:31], v[168:171], v[172:175], v[16:31]
	v_mfma_f32_32x32x16_bf16 v[0:15], v[168:171], v[176:179], v[0:15]
	s_waitcnt vmcnt(6) lgkmcnt(0)
	s_barrier
;     ...
;   for (int kt = 0; kt < nk; ++kt) {
;     if (kt + 1 < nk) asm volatile("s_waitcnt vmcnt(6)" ::: "memory");
;     else asm volatile("s_waitcnt vmcnt(0)" ::: "memory");
;     __builtin_amdgcn_s_barrier();
;     asm volatile("" ::: "memory");
;     if (kt + 2 < nk) { const int st2 = (st >= 1) ? st - 1 : 2; GEMM_ISSUE(kt + 2, st2); }
;     const char* la = lds + st * STAGE_B;
;     const char* lb = la + 32768;
;     const unsigned sa_u = (unsigned)(size_t)la + arow_u, sb_u = (unsigned)(size_t)lb + brow_u;
;     const unsigned a0 = sa_u + co0, a1 = sa_u + co1, a2 = sa_u + co2, a3 = sa_u + co3;
;     const unsigned b0 = sb_u + co0, b1 = sb_u + co1, b2 = sb_u + co2, b3 = sb_u + co3;
;     {
;       bf16x8 p0, p1, q0, q1, u0, u1, w0, w1;
;       asm volatile(
;         "ds_read_b128 %4, %12\n\tds_read_b128 %5, %12 offset:4096\n\tds_read_b128 %6, %16\n\tds_read_b128 %7, %16 offset:4096\n\t"
;         "ds_read_b128 %8, %13\n\tds_read_b128 %9, %13 offset:4096\n\tds_read_b128 %10, %17\n\tds_read_b128 %11, %17 offset:4096\n\t"
;         "s_waitcnt lgkmcnt(4)\n\t"
;         "v_mfma_f32_32x32x16_bf16 %0, %4, %6, %0\n\tv_mfma_f32_32x32x16_bf16 %1, %4, %7, %1\n\tv_mfma_f32_32x32x16_bf16 %2, %5, %6, %2\n\tv_mfma_f32_32x32x16_bf16 %3, %5, %7, %3\n\t"
;         "ds_read_b128 %4, %14\n\tds_read_b128 %5, %14 offset:4096\n\tds_read_b128 %6, %18\n\tds_read_b128 %7, %18 offset:4096\n\t"
;         "s_waitcnt lgkmcnt(4)\n\t"
;         "v_mfma_f32_32x32x16_bf16 %0, %8, %10, %0\n\tv_mfma_f32_32x32x16_bf16 %1, %8, %11, %1\n\tv_mfma_f32_32x32x16_bf16 %2, %9, %10, %2\n\tv_mfma_f32_32x32x16_bf16 %3, %9, %11, %3\n\t"
;         "ds_read_b128 %8, %15\n\tds_read_b128 %9, %15 offset:4096\n\tds_read_b128 %10, %19\n\tds_read_b128 %11, %19 offset:4096\n\t"
;         "s_waitcnt lgkmcnt(4)\n\t"
;         "v_mfma_f32_32x32x16_bf16 %0, %4, %6, %0\n\tv_mfma_f32_32x32x16_bf16 %1, %4, %7, %1\n\tv_mfma_f32_32x32x16_bf16 %2, %5, %6, %2\n\tv_mfma_f32_32x32x16_bf16 %3, %5, %7, %3\n\t"
;         "s_waitcnt lgkmcnt(0)\n\t"
;         "v_mfma_f32_32x32x16_bf16 %0, %8, %10, %0\n\tv_mfma_f32_32x32x16_bf16 %1, %8, %11, %1\n\tv_mfma_f32_32x32x16_bf16 %2, %9, %10, %2\n\tv_mfma_f32_32x32x16_bf16 %3, %9, %11, %3"
;         : "+v"(acc[0][0]), "+v"(acc[0][1]), "+v"(acc[1][0]), "+v"(acc[1][1]),
;           "=&v"(p0), "=&v"(p1), "=&v"(q0), "=&v"(q1), "=&v"(u0), "=&v"(u1), "=&v"(w0), "=&v"(w1)
	ds_read_b128 v[164:167], v144 offset:49152
	ds_read_b128 v[168:171], v144 offset:53248
	ds_read_b128 v[172:175], v148 offset:49152
	ds_read_b128 v[176:179], v148 offset:53248
	v_mfma_f32_32x32x16_bf16 v[48:63], v[180:183], v[218:221], v[48:63]
	s_mov_b32 s64, 0x65c2600
	s_mov_b32 m0, s25
	v_lshl_add_u64 v[226:227], v[142:143], 0, s[64:65]
	global_load_lds_dwordx4 v[226:227], off
	v_mfma_f32_32x32x16_bf16 v[32:47], v[180:183], v[222:225], v[32:47]
	v_mfma_f32_32x32x16_bf16 v[16:31], v[184:187], v[218:221], v[16:31]
	s_add_u32 m0, s25, 0x2000
	v_lshl_add_u64 v[228:229], v[140:141], 0, s[64:65]
	global_load_lds_dwordx4 v[228:229], off
	v_mfma_f32_32x32x16_bf16 v[0:15], v[184:187], v[222:225], v[0:15]
	ds_read_b128 v[180:183], v145 offset:49152
	ds_read_b128 v[184:187], v145 offset:53248
	ds_read_b128 v[218:221], v149 offset:49152
	ds_read_b128 v[222:225], v149 offset:53248
	s_waitcnt lgkmcnt(4)
	v_mfma_f32_32x32x16_bf16 v[48:63], v[164:167], v[172:175], v[48:63]
	s_add_u32 m0, s25, 0x4000
	v_lshl_add_u64 v[226:227], v[138:139], 0, s[64:65]
	global_load_lds_dwordx4 v[226:227], off
	v_mfma_f32_32x32x16_bf16 v[32:47], v[164:167], v[176:179], v[32:47]
	v_mfma_f32_32x32x16_bf16 v[16:31], v[168:171], v[172:175], v[16:31]
	s_add_u32 m0, s25, 0x6000
	v_lshl_add_u64 v[228:229], v[136:137], 0, s[64:65]
	global_load_lds_dwordx4 v[228:229], off
	v_mfma_f32_32x32x16_bf16 v[0:15], v[168:171], v[176:179], v[0:15]
	ds_read_b128 v[164:167], v146 offset:49152
	ds_read_b128 v[168:171], v146 offset:53248
	ds_read_b128 v[172:175], v150 offset:49152
	ds_read_b128 v[176:179], v150 offset:53248
	s_waitcnt lgkmcnt(4)
	v_mfma_f32_32x32x16_bf16 v[48:63], v[180:183], v[218:221], v[48:63]
	s_mov_b32 s64, 0x2740600
	s_add_u32 m0, s25, 0x8000
	v_lshl_add_u64 v[226:227], v[134:135], 0, s[64:65]
	global_load_lds_dwordx4 v[226:227], off
	v_mfma_f32_32x32x16_bf16 v[32:47], v[180:183], v[222:225], v[32:47]
	v_mfma_f32_32x32x16_bf16 v[16:31], v[184:187], v[218:221], v[16:31]
	s_add_u32 m0, s25, 0xa000
	v_lshl_add_u64 v[228:229], v[132:133], 0, s[64:65]
	global_load_lds_dwordx4 v[228:229], off
	v_mfma_f32_32x32x16_bf16 v[0:15], v[184:187], v[222:225], v[0:15]
	ds_read_b128 v[180:183], v147 offset:49152
	ds_read_b128 v[184:187], v147 offset:53248
	ds_read_b128 v[218:221], v151 offset:49152
	ds_read_b128 v[222:225], v151 offset:53248
	s_waitcnt lgkmcnt(4)
	v_mfma_f32_32x32x16_bf16 v[48:63], v[164:167], v[172:175], v[48:63]
	v_mfma_f32_32x32x16_bf16 v[32:47], v[164:167], v[176:179], v[32:47]
	v_mfma_f32_32x32x16_bf16 v[16:31], v[168:171], v[172:175], v[16:31]
	v_mfma_f32_32x32x16_bf16 v[0:15], v[168:171], v[176:179], v[0:15]
	s_waitcnt vmcnt(6) lgkmcnt(0)
	s_barrier
	ds_read_b128 v[164:167], v152
	ds_read_b128 v[168:171], v152 offset:4096
	ds_read_b128 v[172:175], v157
	ds_read_b128 v[176:179], v157 offset:4096
	v_mfma_f32_32x32x16_bf16 v[48:63], v[180:183], v[218:221], v[48:63]
	s_mov_b32 s64, 0x65c2680
	s_add_u32 m0, s25, 0xc000
	v_lshl_add_u64 v[226:227], v[142:143], 0, s[64:65]
	global_load_lds_dwordx4 v[226:227], off
	v_mfma_f32_32x32x16_bf16 v[32:47], v[180:183], v[222:225], v[32:47]
	v_mfma_f32_32x32x16_bf16 v[16:31], v[184:187], v[218:221], v[16:31]
	s_add_u32 m0, s25, 0xe000
	v_lshl_add_u64 v[228:229], v[140:141], 0, s[64:65]
	global_load_lds_dwordx4 v[228:229], off
	v_mfma_f32_32x32x16_bf16 v[0:15], v[184:187], v[222:225], v[0:15]
	ds_read_b128 v[180:183], v153
	ds_read_b128 v[184:187], v153 offset:4096
	ds_read_b128 v[218:221], v158
	ds_read_b128 v[222:225], v158 offset:4096
	s_waitcnt lgkmcnt(4)
	v_mfma_f32_32x32x16_bf16 v[48:63], v[164:167], v[172:175], v[48:63]
	s_add_u32 m0, s25, 0x10000
	v_lshl_add_u64 v[226:227], v[138:139], 0, s[64:65]
	global_load_lds_dwordx4 v[226:227], off
	v_mfma_f32_32x32x16_bf16 v[32:47], v[164:167], v[176:179], v[32:47]
	v_mfma_f32_32x32x16_bf16 v[16:31], v[168:171], v[172:175], v[16:31]
	s_add_u32 m0, s25, 0x12000
	v_lshl_add_u64 v[228:229], v[136:137], 0, s[64:65]
	global_load_lds_dwordx4 v[228:229], off
	v_mfma_f32_32x32x16_bf16 v[0:15], v[168:171], v[176:179], v[0:15]
	ds_read_b128 v[164:167], v154
	ds_read_b128 v[168:171], v154 offset:4096
	ds_read_b128 v[172:175], v159
	ds_read_b128 v[176:179], v159 offset:4096
	s_waitcnt lgkmcnt(4)
	v_mfma_f32_32x32x16_bf16 v[48:63], v[180:183], v[218:221], v[48:63]
	s_mov_b32 s64, 0x2740680
	s_add_u32 m0, s25, 0x14000
	v_lshl_add_u64 v[226:227], v[134:135], 0, s[64:65]
	global_load_lds_dwordx4 v[226:227], off
	v_mfma_f32_32x32x16_bf16 v[32:47], v[180:183], v[222:225], v[32:47]
	v_mfma_f32_32x32x16_bf16 v[16:31], v[184:187], v[218:221], v[16:31]
	s_add_u32 m0, s25, 0x16000
	v_lshl_add_u64 v[228:229], v[132:133], 0, s[64:65]
	global_load_lds_dwordx4 v[228:229], off
	v_mfma_f32_32x32x16_bf16 v[0:15], v[184:187], v[222:225], v[0:15]
	ds_read_b128 v[180:183], v155
	ds_read_b128 v[184:187], v155 offset:4096
	ds_read_b128 v[218:221], v160
	ds_read_b128 v[222:225], v160 offset:4096
	s_waitcnt lgkmcnt(4)
	v_mfma_f32_32x32x16_bf16 v[48:63], v[164:167], v[172:175], v[48:63]
	v_mfma_f32_32x32x16_bf16 v[32:47], v[164:167], v[176:179], v[32:47]
	v_mfma_f32_32x32x16_bf16 v[16:31], v[168:171], v[172:175], v[16:31]
	v_mfma_f32_32x32x16_bf16 v[0:15], v[168:171], v[176:179], v[0:15]
	s_waitcnt vmcnt(6) lgkmcnt(0)
	s_barrier
;     ...
;   for (int kt = 0; kt < nk; ++kt) {
;     if (kt + 1 < nk) asm volatile("s_waitcnt vmcnt(6)" ::: "memory");
;     else asm volatile("s_waitcnt vmcnt(0)" ::: "memory");
;     __builtin_amdgcn_s_barrier();
;     asm volatile("" ::: "memory");
;     if (kt + 2 < nk) { const int st2 = (st >= 1) ? st - 1 : 2; GEMM_ISSUE(kt + 2, st2); }
;     const char* la = lds + st * STAGE_B;
;     const char* lb = la + 32768;
;     const unsigned sa_u = (unsigned)(size_t)la + arow_u, sb_u = (unsigned)(size_t)lb + brow_u;
;     const unsigned a0 = sa_u + co0, a1 = sa_u + co1, a2 = sa_u + co2, a3 = sa_u + co3;
;     const unsigned b0 = sb_u + co0, b1 = sb_u + co1, b2 = sb_u + co2, b3 = sb_u + co3;
;     {
;       bf16x8 p0, p1, q0, q1, u0, u1, w0, w1;
;       asm volatile(
;         "ds_read_b128 %4, %12\n\tds_read_b128 %5, %12 offset:4096\n\tds_read_b128 %6, %16\n\tds_read_b128 %7, %16 offset:4096\n\t"
;         "ds_read_b128 %8, %13\n\tds_read_b128 %9, %13 offset:4096\n\tds_read_b128 %10, %17\n\tds_read_b128 %11, %17 offset:4096\n\t"
;         "s_waitcnt lgkmcnt(4)\n\t"
;         "v_mfma_f32_32x32x16_bf16 %0, %4, %6, %0\n\tv_mfma_f32_32x32x16_bf16 %1, %4, %7, %1\n\tv_mfma_f32_32x32x16_bf16 %2, %5, %6, %2\n\tv_mfma_f32_32x32x16_bf16 %3, %5, %7, %3\n\t"
;         "ds_read_b128 %4, %14\n\tds_read_b128 %5, %14 offset:4096\n\tds_read_b128 %6, %18\n\tds_read_b128 %7, %18 offset:4096\n\t"
;         "s_waitcnt lgkmcnt(4)\n\t"
;         "v_mfma_f32_32x32x16_bf16 %0, %8, %10, %0\n\tv_mfma_f32_32x32x16_bf16 %1, %8, %11, %1\n\tv_mfma_f32_32x32x16_bf16 %2, %9, %10, %2\n\tv_mfma_f32_32x32x16_bf16 %3, %9, %11, %3\n\t"
;         "ds_read_b128 %8, %15\n\tds_read_b128 %9, %15 offset:4096\n\tds_read_b128 %10, %19\n\tds_read_b128 %11, %19 offset:4096\n\t"
;         "s_waitcnt lgkmcnt(4)\n\t"
;         "v_mfma_f32_32x32x16_bf16 %0, %4, %6, %0\n\tv_mfma_f32_32x32x16_bf16 %1, %4, %7, %1\n\tv_mfma_f32_32x32x16_bf16 %2, %5, %6, %2\n\tv_mfma_f32_32x32x16_bf16 %3, %5, %7, %3\n\t"
;         "s_waitcnt lgkmcnt(0)\n\t"
;         "v_mfma_f32_32x32x16_bf16 %0, %8, %10, %0\n\tv_mfma_f32_32x32x16_bf16 %1, %8, %11, %1\n\tv_mfma_f32_32x32x16_bf16 %2, %9, %10, %2\n\tv_mfma_f32_32x32x16_bf16 %3, %9, %11, %3"
;         : "+v"(acc[0][0]), "+v"(acc[0][1]), "+v"(acc[1][0]), "+v"(acc[1][1]),
;           "=&v"(p0), "=&v"(p1), "=&v"(q0), "=&v"(q1), "=&v"(u0), "=&v"(u1), "=&v"(w0), "=&v"(w1)
	ds_read_b128 v[164:167], v144
	ds_read_b128 v[168:171], v144 offset:4096
	ds_read_b128 v[172:175], v148
	ds_read_b128 v[176:179], v148 offset:4096
	v_mfma_f32_32x32x16_bf16 v[48:63], v[180:183], v[218:221], v[48:63]
	s_mov_b32 s64, 0x65c2700
	s_add_u32 m0, s25, 0x18000
	v_lshl_add_u64 v[226:227], v[142:143], 0, s[64:65]
	global_load_lds_dwordx4 v[226:227], off
	v_mfma_f32_32x32x16_bf16 v[32:47], v[180:183], v[222:225], v[32:47]
	v_mfma_f32_32x32x16_bf16 v[16:31], v[184:187], v[218:221], v[16:31]
	s_add_u32 m0, s25, 0x1a000
	v_lshl_add_u64 v[228:229], v[140:141], 0, s[64:65]
	global_load_lds_dwordx4 v[228:229], off
	v_mfma_f32_32x32x16_bf16 v[0:15], v[184:187], v[222:225], v[0:15]
	ds_read_b128 v[180:183], v145
	ds_read_b128 v[184:187], v145 offset:4096
	ds_read_b128 v[218:221], v149
	ds_read_b128 v[222:225], v149 offset:4096
	s_waitcnt lgkmcnt(4)
	v_mfma_f32_32x32x16_bf16 v[48:63], v[164:167], v[172:175], v[48:63]
	s_add_u32 m0, s25, 0x1c000
	v_lshl_add_u64 v[226:227], v[138:139], 0, s[64:65]
	global_load_lds_dwordx4 v[226:227], off
	v_mfma_f32_32x32x16_bf16 v[32:47], v[164:167], v[176:179], v[32:47]
	v_mfma_f32_32x32x16_bf16 v[16:31], v[168:171], v[172:175], v[16:31]
	s_add_u32 m0, s25, 0x1e000
	v_lshl_add_u64 v[228:229], v[136:137], 0, s[64:65]
	global_load_lds_dwordx4 v[228:229], off
	v_mfma_f32_32x32x16_bf16 v[0:15], v[168:171], v[176:179], v[0:15]
	ds_read_b128 v[164:167], v146
	ds_read_b128 v[168:171], v146 offset:4096
	ds_read_b128 v[172:175], v150
	ds_read_b128 v[176:179], v150 offset:4096
	s_waitcnt lgkmcnt(4)
	v_mfma_f32_32x32x16_bf16 v[48:63], v[180:183], v[218:221], v[48:63]
	s_mov_b32 s64, 0x2740700
	s_add_u32 m0, s25, 0x20000
	v_lshl_add_u64 v[226:227], v[134:135], 0, s[64:65]
	global_load_lds_dwordx4 v[226:227], off
	v_mfma_f32_32x32x16_bf16 v[32:47], v[180:183], v[222:225], v[32:47]
	v_mfma_f32_32x32x16_bf16 v[16:31], v[184:187], v[218:221], v[16:31]
	s_add_u32 m0, s25, 0x22000
	v_lshl_add_u64 v[228:229], v[132:133], 0, s[64:65]
	global_load_lds_dwordx4 v[228:229], off
	v_mfma_f32_32x32x16_bf16 v[0:15], v[184:187], v[222:225], v[0:15]
	ds_read_b128 v[180:183], v147
	ds_read_b128 v[184:187], v147 offset:4096
	ds_read_b128 v[218:221], v151
	ds_read_b128 v[222:225], v151 offset:4096
	s_waitcnt lgkmcnt(4)
	v_mfma_f32_32x32x16_bf16 v[48:63], v[164:167], v[172:175], v[48:63]
	v_mfma_f32_32x32x16_bf16 v[32:47], v[164:167], v[176:179], v[32:47]
	v_mfma_f32_32x32x16_bf16 v[16:31], v[168:171], v[172:175], v[16:31]
	v_mfma_f32_32x32x16_bf16 v[0:15], v[168:171], v[176:179], v[0:15]
	s_waitcnt vmcnt(6) lgkmcnt(0)
	s_barrier
	ds_read_b128 v[164:167], v144 offset:49152
	ds_read_b128 v[168:171], v144 offset:53248
	ds_read_b128 v[172:175], v148 offset:49152
	ds_read_b128 v[176:179], v148 offset:53248
	v_mfma_f32_32x32x16_bf16 v[48:63], v[180:183], v[218:221], v[48:63]
	s_mov_b32 s64, 0x65c2780
	s_mov_b32 m0, s25
	v_lshl_add_u64 v[226:227], v[142:143], 0, s[64:65]
	global_load_lds_dwordx4 v[226:227], off
	v_mfma_f32_32x32x16_bf16 v[32:47], v[180:183], v[222:225], v[32:47]
	v_mfma_f32_32x32x16_bf16 v[16:31], v[184:187], v[218:221], v[16:31]
	s_add_u32 m0, s25, 0x2000
	v_lshl_add_u64 v[228:229], v[140:141], 0, s[64:65]
	global_load_lds_dwordx4 v[228:229], off
	v_mfma_f32_32x32x16_bf16 v[0:15], v[184:187], v[222:225], v[0:15]
	ds_read_b128 v[180:183], v145 offset:49152
	ds_read_b128 v[184:187], v145 offset:53248
	ds_read_b128 v[218:221], v149 offset:49152
	ds_read_b128 v[222:225], v149 offset:53248
	s_waitcnt lgkmcnt(4)
	v_mfma_f32_32x32x16_bf16 v[48:63], v[164:167], v[172:175], v[48:63]
	s_add_u32 m0, s25, 0x4000
	v_lshl_add_u64 v[226:227], v[138:139], 0, s[64:65]
	global_load_lds_dwordx4 v[226:227], off
	v_mfma_f32_32x32x16_bf16 v[32:47], v[164:167], v[176:179], v[32:47]
	v_mfma_f32_32x32x16_bf16 v[16:31], v[168:171], v[172:175], v[16:31]
	s_add_u32 m0, s25, 0x6000
	v_lshl_add_u64 v[228:229], v[136:137], 0, s[64:65]
	global_load_lds_dwordx4 v[228:229], off
	v_mfma_f32_32x32x16_bf16 v[0:15], v[168:171], v[176:179], v[0:15]
	ds_read_b128 v[164:167], v146 offset:49152
	ds_read_b128 v[168:171], v146 offset:53248
	ds_read_b128 v[172:175], v150 offset:49152
	ds_read_b128 v[176:179], v150 offset:53248
	s_waitcnt lgkmcnt(4)
	v_mfma_f32_32x32x16_bf16 v[48:63], v[180:183], v[218:221], v[48:63]
	s_mov_b32 s64, 0x2740780
	s_add_u32 m0, s25, 0x8000
	v_lshl_add_u64 v[226:227], v[134:135], 0, s[64:65]
	global_load_lds_dwordx4 v[226:227], off
	v_mfma_f32_32x32x16_bf16 v[32:47], v[180:183], v[222:225], v[32:47]
	v_mfma_f32_32x32x16_bf16 v[16:31], v[184:187], v[218:221], v[16:31]
	s_add_u32 m0, s25, 0xa000
	v_lshl_add_u64 v[228:229], v[132:133], 0, s[64:65]
	global_load_lds_dwordx4 v[228:229], off
	v_mfma_f32_32x32x16_bf16 v[0:15], v[184:187], v[222:225], v[0:15]
	ds_read_b128 v[180:183], v147 offset:49152
	ds_read_b128 v[184:187], v147 offset:53248
	ds_read_b128 v[218:221], v151 offset:49152
	ds_read_b128 v[222:225], v151 offset:53248
	s_waitcnt lgkmcnt(4)
	v_mfma_f32_32x32x16_bf16 v[48:63], v[164:167], v[172:175], v[48:63]
	v_mfma_f32_32x32x16_bf16 v[32:47], v[164:167], v[176:179], v[32:47]
	v_mfma_f32_32x32x16_bf16 v[16:31], v[168:171], v[172:175], v[16:31]
	v_mfma_f32_32x32x16_bf16 v[0:15], v[168:171], v[176:179], v[0:15]
	s_waitcnt vmcnt(6) lgkmcnt(0)
	s_barrier
;     ...
;   for (int kt = 0; kt < nk; ++kt) {
;     if (kt + 1 < nk) asm volatile("s_waitcnt vmcnt(6)" ::: "memory");
;     else asm volatile("s_waitcnt vmcnt(0)" ::: "memory");
;     __builtin_amdgcn_s_barrier();
;     asm volatile("" ::: "memory");
;     if (kt + 2 < nk) { const int st2 = (st >= 1) ? st - 1 : 2; GEMM_ISSUE(kt + 2, st2); }
;     const char* la = lds + st * STAGE_B;
;     const char* lb = la + 32768;
;     const unsigned sa_u = (unsigned)(size_t)la + arow_u, sb_u = (unsigned)(size_t)lb + brow_u;
;     const unsigned a0 = sa_u + co0, a1 = sa_u + co1, a2 = sa_u + co2, a3 = sa_u + co3;
;     const unsigned b0 = sb_u + co0, b1 = sb_u + co1, b2 = sb_u + co2, b3 = sb_u + co3;
;     {
;       bf16x8 p0, p1, q0, q1, u0, u1, w0, w1;
;       asm volatile(
;         "ds_read_b128 %4, %12\n\tds_read_b128 %5, %12 offset:4096\n\tds_read_b128 %6, %16\n\tds_read_b128 %7, %16 offset:4096\n\t"
;         "ds_read_b128 %8, %13\n\tds_read_b128 %9, %13 offset:4096\n\tds_read_b128 %10, %17\n\tds_read_b128 %11, %17 offset:4096\n\t"
;         "s_waitcnt lgkmcnt(4)\n\t"
;         "v_mfma_f32_32x32x16_bf16 %0, %4, %6, %0\n\tv_mfma_f32_32x32x16_bf16 %1, %4, %7, %1\n\tv_mfma_f32_32x32x16_bf16 %2, %5, %6, %2\n\tv_mfma_f32_32x32x16_bf16 %3, %5, %7, %3\n\t"
;         "ds_read_b128 %4, %14\n\tds_read_b128 %5, %14 offset:4096\n\tds_read_b128 %6, %18\n\tds_read_b128 %7, %18 offset:4096\n\t"
;         "s_waitcnt lgkmcnt(4)\n\t"
;         "v_mfma_f32_32x32x16_bf16 %0, %8, %10, %0\n\tv_mfma_f32_32x32x16_bf16 %1, %8, %11, %1\n\tv_mfma_f32_32x32x16_bf16 %2, %9, %10, %2\n\tv_mfma_f32_32x32x16_bf16 %3, %9, %11, %3\n\t"
;         "ds_read_b128 %8, %15\n\tds_read_b128 %9, %15 offset:4096\n\tds_read_b128 %10, %19\n\tds_read_b128 %11, %19 offset:4096\n\t"
;         "s_waitcnt lgkmcnt(4)\n\t"
;         "v_mfma_f32_32x32x16_bf16 %0, %4, %6, %0\n\tv_mfma_f32_32x32x16_bf16 %1, %4, %7, %1\n\tv_mfma_f32_32x32x16_bf16 %2, %5, %6, %2\n\tv_mfma_f32_32x32x16_bf16 %3, %5, %7, %3\n\t"
;         "s_waitcnt lgkmcnt(0)\n\t"
;         "v_mfma_f32_32x32x16_bf16 %0, %8, %10, %0\n\tv_mfma_f32_32x32x16_bf16 %1, %8, %11, %1\n\tv_mfma_f32_32x32x16_bf16 %2, %9, %10, %2\n\tv_mfma_f32_32x32x16_bf16 %3, %9, %11, %3"
;         : "+v"(acc[0][0]), "+v"(acc[0][1]), "+v"(acc[1][0]), "+v"(acc[1][1]),
;           "=&v"(p0), "=&v"(p1), "=&v"(q0), "=&v"(q1), "=&v"(u0), "=&v"(u1), "=&v"(w0), "=&v"(w1)
	ds_read_b128 v[164:167], v152
	ds_read_b128 v[168:171], v152 offset:4096
	ds_read_b128 v[172:175], v157
	ds_read_b128 v[176:179], v157 offset:4096
	v_mfma_f32_32x32x16_bf16 v[48:63], v[180:183], v[218:221], v[48:63]
	v_mfma_f32_32x32x16_bf16 v[32:47], v[180:183], v[222:225], v[32:47]
	v_mfma_f32_32x32x16_bf16 v[16:31], v[184:187], v[218:221], v[16:31]
	v_mfma_f32_32x32x16_bf16 v[0:15], v[184:187], v[222:225], v[0:15]
	ds_read_b128 v[180:183], v153
	ds_read_b128 v[184:187], v153 offset:4096
	ds_read_b128 v[218:221], v158
	ds_read_b128 v[222:225], v158 offset:4096
	s_waitcnt lgkmcnt(4)
	v_mfma_f32_32x32x16_bf16 v[48:63], v[164:167], v[172:175], v[48:63]
	v_mfma_f32_32x32x16_bf16 v[32:47], v[164:167], v[176:179], v[32:47]
	v_mfma_f32_32x32x16_bf16 v[16:31], v[168:171], v[172:175], v[16:31]
	v_mfma_f32_32x32x16_bf16 v[0:15], v[168:171], v[176:179], v[0:15]
	ds_read_b128 v[164:167], v154
	ds_read_b128 v[168:171], v154 offset:4096
	ds_read_b128 v[172:175], v159
	ds_read_b128 v[176:179], v159 offset:4096
	s_waitcnt lgkmcnt(4)
	v_mfma_f32_32x32x16_bf16 v[48:63], v[180:183], v[218:221], v[48:63]
	v_mfma_f32_32x32x16_bf16 v[32:47], v[180:183], v[222:225], v[32:47]
	v_mfma_f32_32x32x16_bf16 v[16:31], v[184:187], v[218:221], v[16:31]
	v_mfma_f32_32x32x16_bf16 v[0:15], v[184:187], v[222:225], v[0:15]
	ds_read_b128 v[180:183], v155
	ds_read_b128 v[184:187], v155 offset:4096
	ds_read_b128 v[218:221], v160
	ds_read_b128 v[222:225], v160 offset:4096
	s_waitcnt lgkmcnt(4)
	v_mfma_f32_32x32x16_bf16 v[48:63], v[164:167], v[172:175], v[48:63]
	v_mfma_f32_32x32x16_bf16 v[32:47], v[164:167], v[176:179], v[32:47]
	v_mfma_f32_32x32x16_bf16 v[16:31], v[168:171], v[172:175], v[16:31]
	v_mfma_f32_32x32x16_bf16 v[0:15], v[168:171], v[176:179], v[0:15]
	s_waitcnt vmcnt(0) lgkmcnt(0)
	s_barrier
	ds_read_b128 v[164:167], v144
	ds_read_b128 v[168:171], v144 offset:4096
	ds_read_b128 v[172:175], v148
	ds_read_b128 v[176:179], v148 offset:4096
	v_mfma_f32_32x32x16_bf16 v[48:63], v[180:183], v[218:221], v[48:63]
	v_mfma_f32_32x32x16_bf16 v[32:47], v[180:183], v[222:225], v[32:47]
	v_mfma_f32_32x32x16_bf16 v[16:31], v[184:187], v[218:221], v[16:31]
	v_mfma_f32_32x32x16_bf16 v[0:15], v[184:187], v[222:225], v[0:15]
	ds_read_b128 v[180:183], v145
	ds_read_b128 v[184:187], v145 offset:4096
	ds_read_b128 v[218:221], v149
	ds_read_b128 v[222:225], v149 offset:4096
	s_waitcnt lgkmcnt(4)
	v_mfma_f32_32x32x16_bf16 v[48:63], v[164:167], v[172:175], v[48:63]
	v_mfma_f32_32x32x16_bf16 v[32:47], v[164:167], v[176:179], v[32:47]
	v_mfma_f32_32x32x16_bf16 v[16:31], v[168:171], v[172:175], v[16:31]
	v_mfma_f32_32x32x16_bf16 v[0:15], v[168:171], v[176:179], v[0:15]
	ds_read_b128 v[164:167], v146
	ds_read_b128 v[168:171], v146 offset:4096
	ds_read_b128 v[172:175], v150
	ds_read_b128 v[176:179], v150 offset:4096
	s_waitcnt lgkmcnt(4)
	v_mfma_f32_32x32x16_bf16 v[48:63], v[180:183], v[218:221], v[48:63]
	v_mfma_f32_32x32x16_bf16 v[32:47], v[180:183], v[222:225], v[32:47]
	v_mfma_f32_32x32x16_bf16 v[16:31], v[184:187], v[218:221], v[16:31]
	v_mfma_f32_32x32x16_bf16 v[0:15], v[184:187], v[222:225], v[0:15]
	ds_read_b128 v[180:183], v147
	ds_read_b128 v[184:187], v147 offset:4096
	ds_read_b128 v[218:221], v151
	ds_read_b128 v[222:225], v151 offset:4096
	s_waitcnt lgkmcnt(4)
	v_mfma_f32_32x32x16_bf16 v[48:63], v[164:167], v[172:175], v[48:63]
	v_mfma_f32_32x32x16_bf16 v[32:47], v[164:167], v[176:179], v[32:47]
	v_mfma_f32_32x32x16_bf16 v[16:31], v[168:171], v[172:175], v[16:31]
	v_mfma_f32_32x32x16_bf16 v[0:15], v[168:171], v[176:179], v[0:15]
	s_waitcnt lgkmcnt(0)
	v_mfma_f32_32x32x16_bf16 v[48:63], v[180:183], v[218:221], v[48:63]
	v_mfma_f32_32x32x16_bf16 v[32:47], v[180:183], v[222:225], v[32:47]
	v_mfma_f32_32x32x16_bf16 v[16:31], v[184:187], v[218:221], v[16:31]
	v_mfma_f32_32x32x16_bf16 v[0:15], v[184:187], v[222:225], v[0:15]
	s_cmp_eq_u32 s11, 1
	s_mov_b32 s26, 0x1810000
	s_movk_i32 s24, 0x100
	s_cselect_b32 s65, s26, 0x1850000
	s_movk_i32 s26, 0x180
	s_cselect_b32 s64, s24, 0x80
	s_cselect_b32 s26, s26, 0x280
	s_nop 15
	v_mul_f32_e32 v48, 0xbfb8aa3b, v48
	v_mul_f32_e32 v49, 0xbfb8aa3b, v49
	v_mul_f32_e32 v50, 0xbfb8aa3b, v50
	v_mul_f32_e32 v51, 0xbfb8aa3b, v51
	v_mul_f32_e32 v52, 0xbfb8aa3b, v52
	v_mul_f32_e32 v53, 0xbfb8aa3b, v53
	v_mul_f32_e32 v54, 0xbfb8aa3b, v54
	v_mul_f32_e32 v55, 0xbfb8aa3b, v55
	v_exp_f32_e32 v48, v48
	v_exp_f32_e32 v49, v49
	v_exp_f32_e32 v50, v50
	v_exp_f32_e32 v51, v51
	v_exp_f32_e32 v52, v52
	v_exp_f32_e32 v53, v53
	v_exp_f32_e32 v54, v54
	v_exp_f32_e32 v55, v55
	v_add_f32_e32 v48, 1.0, v48
	v_add_f32_e32 v49, 1.0, v49
	v_add_f32_e32 v50, 1.0, v50
	v_add_f32_e32 v51, 1.0, v51
	v_add_f32_e32 v52, 1.0, v52
	v_add_f32_e32 v53, 1.0, v53
	v_add_f32_e32 v54, 1.0, v54
	v_add_f32_e32 v55, 1.0, v55
	v_rcp_f32_e32 v48, v48
	v_rcp_f32_e32 v49, v49
	v_rcp_f32_e32 v50, v50
	v_rcp_f32_e32 v51, v51
	v_rcp_f32_e32 v52, v52
	v_rcp_f32_e32 v53, v53
	v_rcp_f32_e32 v54, v54
	v_rcp_f32_e32 v55, v55
	v_cvt_pk_bf16_f32 v144, v48, v49
	v_cvt_pk_bf16_f32 v145, v50, v51
	v_cvt_pk_bf16_f32 v146, v52, v53
	v_cvt_pk_bf16_f32 v147, v54, v55
	v_mul_f32_e32 v56, 0xbfb8aa3b, v56
	v_mul_f32_e32 v57, 0xbfb8aa3b, v57
	v_mul_f32_e32 v58, 0xbfb8aa3b, v58
	v_mul_f32_e32 v59, 0xbfb8aa3b, v59
	v_mul_f32_e32 v60, 0xbfb8aa3b, v60
	v_mul_f32_e32 v61, 0xbfb8aa3b, v61
	v_mul_f32_e32 v62, 0xbfb8aa3b, v62
	v_mul_f32_e32 v63, 0xbfb8aa3b, v63
	v_exp_f32_e32 v56, v56
	v_exp_f32_e32 v57, v57
	v_exp_f32_e32 v58, v58
	v_exp_f32_e32 v59, v59
	v_exp_f32_e32 v60, v60
	v_exp_f32_e32 v61, v61
	v_exp_f32_e32 v62, v62
	v_exp_f32_e32 v63, v63
	v_add_f32_e32 v56, 1.0, v56
	v_add_f32_e32 v57, 1.0, v57
	v_add_f32_e32 v58, 1.0, v58
; DI unsigned pack2(float a, float b) { unsigned r; asm("v_cvt_pk_bf16_f32 %0, %1, %2" : "=v"(r) : "v"(a), "v"(b)); return r; }
; DI float sigmoidf_(float x) { return 1.f / (1.f + __expf(-x)); }
;     ...
;   asm volatile("s_nop 15\n\ts_nop 15\n\ts_nop 7" ::: "memory");
;   __builtin_amdgcn_s_barrier();
; DI void merge_phase(const Params& p, int layer, char* lds) {
;     ...
;       const int kw = (br == 0) ? 384 : (br == 1 ? 256 : 128);
;       const int yo = (br == 0) ? 0 : (br == 1 ? 384 : 640);
;       const bf16_t* wu = wl + ((br == 0) ? OW_UA : (br == 1 ? OW_UB : OW_UC));
;     ...
;             for (int i = 0; i < 8; ++i) sg[a][c][i] = pack2(sigmoidf_(ag[a][c][2 * i]), sigmoidf_(ag[a][c][2 * i + 1]));
	v_add_f32_e32 v59, 1.0, v59
	v_add_f32_e32 v60, 1.0, v60
	v_add_f32_e32 v61, 1.0, v61
	v_add_f32_e32 v62, 1.0, v62
	v_add_f32_e32 v63, 1.0, v63
	v_rcp_f32_e32 v56, v56
	v_rcp_f32_e32 v57, v57
	v_rcp_f32_e32 v58, v58
	v_rcp_f32_e32 v59, v59
	v_rcp_f32_e32 v60, v60
	v_rcp_f32_e32 v61, v61
	v_rcp_f32_e32 v62, v62
	v_rcp_f32_e32 v63, v63
	v_cvt_pk_bf16_f32 v148, v56, v57
	v_cvt_pk_bf16_f32 v149, v58, v59
	v_cvt_pk_bf16_f32 v150, v60, v61
	v_cvt_pk_bf16_f32 v151, v62, v63
	v_mul_f32_e32 v32, 0xbfb8aa3b, v32
	v_mul_f32_e32 v33, 0xbfb8aa3b, v33
	v_mul_f32_e32 v34, 0xbfb8aa3b, v34
	v_mul_f32_e32 v35, 0xbfb8aa3b, v35
	v_mul_f32_e32 v36, 0xbfb8aa3b, v36
	v_mul_f32_e32 v37, 0xbfb8aa3b, v37
	v_mul_f32_e32 v38, 0xbfb8aa3b, v38
	v_mul_f32_e32 v39, 0xbfb8aa3b, v39
	v_exp_f32_e32 v32, v32
	v_exp_f32_e32 v33, v33
	v_exp_f32_e32 v34, v34
	v_exp_f32_e32 v35, v35
	v_exp_f32_e32 v36, v36
	v_exp_f32_e32 v37, v37
	v_exp_f32_e32 v38, v38
	v_exp_f32_e32 v39, v39
	v_add_f32_e32 v32, 1.0, v32
	v_add_f32_e32 v33, 1.0, v33
	v_add_f32_e32 v34, 1.0, v34
	v_add_f32_e32 v35, 1.0, v35
	v_add_f32_e32 v36, 1.0, v36
	v_add_f32_e32 v37, 1.0, v37
	v_add_f32_e32 v38, 1.0, v38
	v_add_f32_e32 v39, 1.0, v39
	v_rcp_f32_e32 v32, v32
	v_rcp_f32_e32 v33, v33
	v_rcp_f32_e32 v34, v34
	v_rcp_f32_e32 v35, v35
	v_rcp_f32_e32 v36, v36
	v_rcp_f32_e32 v37, v37
	v_rcp_f32_e32 v38, v38
	v_rcp_f32_e32 v39, v39
	v_cvt_pk_bf16_f32 v152, v32, v33
	v_cvt_pk_bf16_f32 v153, v34, v35
	v_cvt_pk_bf16_f32 v154, v36, v37
	v_cvt_pk_bf16_f32 v155, v38, v39
	v_mul_f32_e32 v40, 0xbfb8aa3b, v40
	v_mul_f32_e32 v41, 0xbfb8aa3b, v41
	v_mul_f32_e32 v42, 0xbfb8aa3b, v42
	v_mul_f32_e32 v43, 0xbfb8aa3b, v43
	v_mul_f32_e32 v44, 0xbfb8aa3b, v44
	v_mul_f32_e32 v45, 0xbfb8aa3b, v45
	v_mul_f32_e32 v46, 0xbfb8aa3b, v46
	v_mul_f32_e32 v47, 0xbfb8aa3b, v47
	v_exp_f32_e32 v40, v40
	v_exp_f32_e32 v41, v41
	v_exp_f32_e32 v42, v42
	v_exp_f32_e32 v43, v43
	v_exp_f32_e32 v44, v44
	v_exp_f32_e32 v45, v45
	v_exp_f32_e32 v46, v46
	v_exp_f32_e32 v47, v47
	v_add_f32_e32 v40, 1.0, v40
	v_add_f32_e32 v41, 1.0, v41
	v_add_f32_e32 v42, 1.0, v42
	v_add_f32_e32 v43, 1.0, v43
	v_add_f32_e32 v44, 1.0, v44
	v_add_f32_e32 v45, 1.0, v45
	v_add_f32_e32 v46, 1.0, v46
	v_add_f32_e32 v47, 1.0, v47
	v_rcp_f32_e32 v40, v40
	v_rcp_f32_e32 v41, v41
	v_rcp_f32_e32 v42, v42
	v_rcp_f32_e32 v43, v43
	v_rcp_f32_e32 v44, v44
	v_rcp_f32_e32 v45, v45
	v_rcp_f32_e32 v46, v46
	v_rcp_f32_e32 v47, v47
	v_cvt_pk_bf16_f32 v157, v40, v41
	v_cvt_pk_bf16_f32 v158, v42, v43
	v_cvt_pk_bf16_f32 v159, v44, v45
	v_cvt_pk_bf16_f32 v160, v46, v47
	v_mul_f32_e32 v16, 0xbfb8aa3b, v16
	v_mul_f32_e32 v17, 0xbfb8aa3b, v17
	v_mul_f32_e32 v18, 0xbfb8aa3b, v18
	v_mul_f32_e32 v19, 0xbfb8aa3b, v19
	v_mul_f32_e32 v20, 0xbfb8aa3b, v20
	v_mul_f32_e32 v21, 0xbfb8aa3b, v21
	v_mul_f32_e32 v22, 0xbfb8aa3b, v22
	v_mul_f32_e32 v23, 0xbfb8aa3b, v23
	v_exp_f32_e32 v16, v16
	v_exp_f32_e32 v17, v17
	v_exp_f32_e32 v18, v18
	v_exp_f32_e32 v19, v19
	v_exp_f32_e32 v20, v20
	v_exp_f32_e32 v21, v21
	v_exp_f32_e32 v22, v22
	v_exp_f32_e32 v23, v23
	v_add_f32_e32 v16, 1.0, v16
	v_add_f32_e32 v17, 1.0, v17
	v_add_f32_e32 v18, 1.0, v18
	v_add_f32_e32 v19, 1.0, v19
	v_add_f32_e32 v20, 1.0, v20
	v_add_f32_e32 v21, 1.0, v21
	v_add_f32_e32 v22, 1.0, v22
	v_add_f32_e32 v23, 1.0, v23
	v_rcp_f32_e32 v16, v16
	v_rcp_f32_e32 v17, v17
	v_rcp_f32_e32 v18, v18
	v_rcp_f32_e32 v19, v19
	v_rcp_f32_e32 v20, v20
	v_rcp_f32_e32 v21, v21
	v_rcp_f32_e32 v22, v22
	v_rcp_f32_e32 v23, v23
	v_cvt_pk_bf16_f32 v161, v16, v17
	v_cvt_pk_bf16_f32 v162, v18, v19
	v_cvt_pk_bf16_f32 v163, v20, v21
	v_cvt_pk_bf16_f32 v164, v22, v23
	v_mul_f32_e32 v24, 0xbfb8aa3b, v24
	v_mul_f32_e32 v25, 0xbfb8aa3b, v25
	v_mul_f32_e32 v26, 0xbfb8aa3b, v26
	v_mul_f32_e32 v27, 0xbfb8aa3b, v27
	v_mul_f32_e32 v28, 0xbfb8aa3b, v28
	v_mul_f32_e32 v29, 0xbfb8aa3b, v29
	v_mul_f32_e32 v30, 0xbfb8aa3b, v30
	v_mul_f32_e32 v31, 0xbfb8aa3b, v31
	v_exp_f32_e32 v24, v24
	v_exp_f32_e32 v25, v25
	v_exp_f32_e32 v26, v26
	v_exp_f32_e32 v27, v27
	v_exp_f32_e32 v28, v28
	v_exp_f32_e32 v29, v29
	v_exp_f32_e32 v30, v30
	v_exp_f32_e32 v31, v31
	v_add_f32_e32 v24, 1.0, v24
	v_add_f32_e32 v25, 1.0, v25
	v_add_f32_e32 v26, 1.0, v26
	v_add_f32_e32 v27, 1.0, v27
	v_add_f32_e32 v28, 1.0, v28
	v_add_f32_e32 v29, 1.0, v29
	v_add_f32_e32 v30, 1.0, v30
	v_add_f32_e32 v31, 1.0, v31
	v_rcp_f32_e32 v24, v24
	v_rcp_f32_e32 v25, v25
	v_rcp_f32_e32 v26, v26
	v_rcp_f32_e32 v27, v27
	v_rcp_f32_e32 v28, v28
	v_rcp_f32_e32 v29, v29
	v_rcp_f32_e32 v30, v30
	v_rcp_f32_e32 v31, v31
	v_cvt_pk_bf16_f32 v165, v24, v25
	v_cvt_pk_bf16_f32 v166, v26, v27
	v_cvt_pk_bf16_f32 v167, v28, v29
	v_cvt_pk_bf16_f32 v168, v30, v31
	v_mul_f32_e32 v0, 0xbfb8aa3b, v0
	v_mul_f32_e32 v1, 0xbfb8aa3b, v1
	v_mul_f32_e32 v2, 0xbfb8aa3b, v2
	v_mul_f32_e32 v3, 0xbfb8aa3b, v3
	v_mul_f32_e32 v4, 0xbfb8aa3b, v4
	v_mul_f32_e32 v5, 0xbfb8aa3b, v5
	v_mul_f32_e32 v6, 0xbfb8aa3b, v6
	v_mul_f32_e32 v7, 0xbfb8aa3b, v7
	v_exp_f32_e32 v0, v0
	v_exp_f32_e32 v1, v1
	v_exp_f32_e32 v2, v2
	v_exp_f32_e32 v3, v3
	v_exp_f32_e32 v4, v4
	v_exp_f32_e32 v5, v5
	v_exp_f32_e32 v6, v6
	v_exp_f32_e32 v7, v7
	v_add_f32_e32 v0, 1.0, v0
	v_add_f32_e32 v1, 1.0, v1
	v_add_f32_e32 v2, 1.0, v2
	v_add_f32_e32 v3, 1.0, v3
	v_add_f32_e32 v4, 1.0, v4
	v_add_f32_e32 v5, 1.0, v5
	v_add_f32_e32 v6, 1.0, v6
	v_add_f32_e32 v7, 1.0, v7
	v_rcp_f32_e32 v0, v0
	v_rcp_f32_e32 v1, v1
	v_rcp_f32_e32 v2, v2
	v_rcp_f32_e32 v3, v3
	v_rcp_f32_e32 v4, v4
	v_rcp_f32_e32 v5, v5
	v_rcp_f32_e32 v6, v6
	v_rcp_f32_e32 v7, v7
	v_cvt_pk_bf16_f32 v169, v0, v1
	v_cvt_pk_bf16_f32 v170, v2, v3
	v_cvt_pk_bf16_f32 v171, v4, v5
	v_cvt_pk_bf16_f32 v172, v6, v7
	v_mul_f32_e32 v8, 0xbfb8aa3b, v8
	v_mul_f32_e32 v9, 0xbfb8aa3b, v9
	v_mul_f32_e32 v10, 0xbfb8aa3b, v10
	v_mul_f32_e32 v11, 0xbfb8aa3b, v11
	v_mul_f32_e32 v12, 0xbfb8aa3b, v12
	v_mul_f32_e32 v13, 0xbfb8aa3b, v13
	v_mul_f32_e32 v14, 0xbfb8aa3b, v14
	v_mul_f32_e32 v15, 0xbfb8aa3b, v15
	v_exp_f32_e32 v8, v8
	v_exp_f32_e32 v9, v9
	v_exp_f32_e32 v10, v10
	v_exp_f32_e32 v11, v11
	v_exp_f32_e32 v12, v12
	v_exp_f32_e32 v13, v13
	v_exp_f32_e32 v14, v14
	v_exp_f32_e32 v15, v15
	v_add_f32_e32 v8, 1.0, v8
	v_add_f32_e32 v9, 1.0, v9
	v_add_f32_e32 v10, 1.0, v10
	v_add_f32_e32 v11, 1.0, v11
	v_add_f32_e32 v12, 1.0, v12
	v_add_f32_e32 v13, 1.0, v13
	v_add_f32_e32 v14, 1.0, v14
	v_add_f32_e32 v15, 1.0, v15
	v_rcp_f32_e32 v8, v8
	v_rcp_f32_e32 v9, v9
	v_rcp_f32_e32 v10, v10
	v_rcp_f32_e32 v11, v11
	v_rcp_f32_e32 v12, v12
	v_rcp_f32_e32 v13, v13
	v_rcp_f32_e32 v14, v14
	v_rcp_f32_e32 v15, v15
	v_cvt_pk_bf16_f32 v173, v8, v9
	v_cvt_pk_bf16_f32 v174, v10, v11
	v_cvt_pk_bf16_f32 v175, v12, v13
	v_cvt_pk_bf16_f32 v176, v14, v15
	s_cmp_eq_u32 s11, 0
	s_cselect_b32 s27, 0x17b0000, s65
	s_cselect_b32 s64, 0x180, s64
	s_cselect_b32 s26, 0, s26
	s_lshl_b32 s65, s27, 1
	s_add_u32 vcc_lo, s4, s65
	s_addc_u32 vcc_hi, s22, 0
	s_lshl_b32 s24, s26, 1
	s_add_u32 s26, s9, s24
	s_mul_i32 s25, s57, s64
	s_mul_hi_u32 s30, s56, s64
	v_mov_b32_e32 v1, v129
	s_nop 15
	s_nop 15
	s_nop 7
	s_barrier
; #define TIDX get_tid_()
; #define GEMM_ISSUE(kt_, st_) do { char* sb_ = lw + (st_) * STAGE_B; const char* ak_ = Ab + (size_t)(kt_) * 128; const char* bk_ = Bb + (size_t)(kt_) * 128; \
;     _Pragma("unroll") for (int i_ = 0; i_ < 4; ++i_) glds16(ak_ + avo[i_], sb_ + i_ * 8192); \
;     _Pragma("unroll") for (int i_ = 0; i_ < 2; ++i_) glds16(bk_ + bvo[i_], sb_ + 32768 + i_ * 8192); } while (0)
;   const int tid = TIDX, lane = tid & 63, wid = tid >> 6, wr = wid >> 1, wc = wid & 1, r = lane & 31, h = lane >> 5;
;   const int ch = (tid & 7) ^ ((tid >> 4) & 7);
;   unsigned avo[4], bvo[2];
; #pragma unroll
;   for (int i = 0; i < 4; ++i) avo[i] = (unsigned)(((tid >> 3) + 64 * i) * lda * 2 + ch * 16);
; #pragma unroll
;   for (int i = 0; i < 2; ++i) bvo[i] = (unsigned)(((tid >> 3) + 64 * i) * ldb * 2 + ch * 16);
;   const char* Ab = (const char*)A; const char* Bb = (const char*)Bt;
;   char* lw = lds + tid * 16;
;   const int nk = K >> 6;
;   const unsigned swz = (unsigned)((r >> 1) & 7);
;   const unsigned arow_u = (unsigned)((wr * 64 + r) * 128), brow_u = (unsigned)((wc * 64 + r) * 128);
;   const unsigned co0 = ((0u + h) ^ swz) << 4, co1 = ((2u + h) ^ swz) << 4, co2 = ((4u + h) ^ swz) << 4, co3 = ((6u + h) ^ swz) << 4;
;     ...
;   if (PART != 2) {
;     GEMM_ISSUE(0, 0);
;     if (nk > 1) GEMM_ISSUE(1, 1);
;   }
; DI void merge_phase(const Params& p, int layer, char* lds) {
;     ...
;       f32x16 au[2][2];
;       zero_acc(au);
;       gemm_core(y + (size_t)mt * 256 * 768 + yo, 768, wu + (size_t)nt * 128 * kw, kw, kw, au, lds);
	s_addc_u32 s27, s15, 0
	s_add_i32 s31, s30, s25
	s_movk_i32 s25, 0x70
	v_lshlrev_b32_e32 v5, 4, v1
	v_ashrrev_i32_e32 v22, 3, v1
	v_bitop3_b32 v23, v5, s25, v1 bitop3:0x48
	s_movk_i32 s25, 0x600
	v_lshrrev_b32_e32 v3, 5, v1
	v_mul_lo_u32 v0, v22, s25
	v_and_b32_e32 v7, 31, v1
	v_add_u32_e32 v177, 0, v5
	v_lshrrev_b32_e32 v5, 1, v1
	v_bfe_u32 v10, v1, 1, 3
	s_mov_b32 s25, 0x1ffffc0
	v_and_or_b32 v7, v5, s25, v7
	v_bitop3_b32 v18, v3, v10, 1 bitop3:0x6c
	v_readfirstlane_b32 s25, v177
	v_add_u32_e32 v3, 0x2000, v177
	s_mul_i32 s30, s56, s64
	v_or_b32_e32 v130, v23, v0
	v_mul_lo_u32 v6, s64, v22
	v_bfe_u32 v9, v1, 5, 1
	s_mov_b32 m0, s25
	v_readfirstlane_b32 s25, v3
	v_add_u32_e32 v5, 0x4000, v177
	s_lshl_b64 s[30:31], s[30:31], 1
	v_add_u32_e32 v0, 0x18000, v130
	v_lshlrev_b32_e32 v8, 1, v6
	v_bitop3_b32 v25, v9, v10, 2 bitop3:0x36
	v_bitop3_b32 v19, v9, v10, 4 bitop3:0x36
	v_bitop3_b32 v26, v9, v10, 6 bitop3:0x36
	global_load_lds_dwordx4 v130, s[26:27]
	s_mov_b32 m0, s25
	v_readfirstlane_b32 s25, v5
	v_add_u32_e32 v9, 0x6000, v177
	s_add_u32 s30, vcc_lo, s30
	v_add_u32_e32 v2, 0x30000, v130
	v_or_b32_e32 v6, v23, v8
	v_lshl_add_u32 v8, s64, 7, v8
	global_load_lds_dwordx4 v0, s[26:27]
	s_mov_b32 m0, s25
	v_readfirstlane_b32 s25, v9
	v_add_u32_e32 v9, 0x8000, v177
	s_addc_u32 s31, vcc_hi, s31
	v_or_b32_e32 v8, v8, v23
	global_load_lds_dwordx4 v2, s[26:27]
	s_mov_b32 m0, s25
	v_readfirstlane_b32 s25, v9
	v_mov_b32_e32 v9, v131
	v_add_u32_e32 v4, 0x48000, v130
	v_lshl_add_u64 v[20:21], s[30:31], 0, v[8:9]
	v_add_u32_e32 v9, 0xa000, v177
	global_load_lds_dwordx4 v4, s[26:27]
	s_mov_b32 m0, s25
	v_readfirstlane_b32 s25, v9
	v_lshl_add_u64 v[10:11], s[26:27], 0, v[130:131]
	global_load_lds_dwordx4 v6, s[30:31]
	s_mov_b32 m0, s25
	v_lshlrev_b32_e32 v181, 4, v25
	v_add_u32_e32 v25, 0xc000, v177
	v_lshlrev_b32_e32 v24, 7, v1
	v_mov_b32_e32 v1, v131
	global_load_lds_dwordx4 v8, s[30:31]
	v_lshl_add_u64 v[8:9], v[10:11], 0, s[92:93]
	v_readfirstlane_b32 s25, v25
	v_add_u32_e32 v10, 0xe000, v177
	v_lshl_add_u64 v[12:13], s[26:27], 0, v[0:1]
	v_mov_b32_e32 v3, v131
	s_mov_b32 m0, s25
	v_readfirstlane_b32 s25, v10
	v_add_u32_e32 v10, 0x10000, v177
	v_lshl_add_u64 v[14:15], s[26:27], 0, v[2:3]
	v_mov_b32_e32 v5, v131
	global_load_lds_dwordx4 v[8:9], off
	v_lshl_add_u64 v[8:9], v[12:13], 0, s[92:93]
	s_mov_b32 m0, s25
	v_readfirstlane_b32 s25, v10
	v_add_u32_e32 v10, 0x12000, v177
	v_lshl_add_u64 v[16:17], s[26:27], 0, v[4:5]
	v_lshlrev_b32_e32 v180, 7, v7
	v_mov_b32_e32 v7, v131
	global_load_lds_dwordx4 v[8:9], off
	v_lshl_add_u64 v[8:9], v[14:15], 0, s[92:93]
	s_mov_b32 m0, s25
	v_readfirstlane_b32 s25, v10
	v_add_u32_e32 v10, 0x14000, v177
	v_lshlrev_b32_e32 v179, 4, v18
	v_lshlrev_b32_e32 v178, 4, v19
	v_lshl_add_u64 v[18:19], s[30:31], 0, v[6:7]
	global_load_lds_dwordx4 v[8:9], off
	v_lshl_add_u64 v[8:9], v[16:17], 0, s[92:93]
	s_mov_b32 m0, s25
	v_readfirstlane_b32 s25, v10
	v_add_u32_e32 v10, 0x16000, v177
	global_load_lds_dwordx4 v[8:9], off
	v_lshl_add_u64 v[8:9], v[18:19], 0, s[92:93]
	s_mov_b32 m0, s25
	v_readfirstlane_b32 s25, v10
	global_load_lds_dwordx4 v[8:9], off
	v_lshl_add_u64 v[8:9], v[20:21], 0, s[92:93]
	s_mov_b32 m0, s25
	s_lshr_b32 s26, s64, 6
	global_load_lds_dwordx4 v[8:9], off
	s_add_u32 s30, s69, s24
	s_mul_i32 s24, s61, s64
	s_mul_hi_u32 s25, s60, s64
	s_addc_u32 s31, s70, 0
	s_add_i32 s25, s25, s24
	s_mul_i32 s24, s60, s64
	s_add_u32 s24, s67, s24
	v_lshl_add_u64 v[134:135], s[30:31], 0, v[0:1]
	s_addc_u32 s25, s23, s25
	v_lshl_add_u32 v0, v22, 1, v196
	v_lshl_add_u64 v[132:133], s[30:31], 0, v[130:131]
	v_lshl_add_u64 v[136:137], s[30:31], 0, v[2:3]
	v_lshl_add_u64 v[138:139], s[30:31], 0, v[4:5]
	s_add_u32 s30, s24, s65
	v_mul_lo_u32 v0, s64, v0
	s_addc_u32 s31, s25, 0
	v_or_b32_e32 v130, v0, v23
	v_mov_b32_e32 v0, 0
	s_mov_b32 s63, 0
	s_mov_b32 s71, 1
	v_and_b32_e32 v182, 0x2f80, v24
	v_lshlrev_b32_e32 v183, 4, v26
	v_lshl_add_u64 v[140:141], s[30:31], 0, v[6:7]
	v_lshl_add_u64 v[142:143], s[30:31], 0, v[130:131]
	v_mov_b32_e32 v1, v0
	v_mov_b32_e32 v2, v0
	v_mov_b32_e32 v3, v0
	v_mov_b32_e32 v4, v0
	v_mov_b32_e32 v5, v0
	v_mov_b32_e32 v6, v0
	v_mov_b32_e32 v7, v0
	v_mov_b32_e32 v8, v0
	v_mov_b32_e32 v9, v0
	v_mov_b32_e32 v10, v0
	v_mov_b32_e32 v11, v0
	v_mov_b32_e32 v12, v0
	v_mov_b32_e32 v13, v0
	v_mov_b32_e32 v14, v0
	v_mov_b32_e32 v15, v0
	v_mov_b32_e32 v16, v0
	v_mov_b32_e32 v17, v0
	v_mov_b32_e32 v18, v0
	v_mov_b32_e32 v19, v0
	v_mov_b32_e32 v20, v0
	v_mov_b32_e32 v21, v0
	v_mov_b32_e32 v22, v0
	v_mov_b32_e32 v23, v0
	v_mov_b32_e32 v24, v0
	v_mov_b32_e32 v25, v0
	v_mov_b32_e32 v26, v0
	v_mov_b32_e32 v27, v0
	v_mov_b32_e32 v28, v0
	v_mov_b32_e32 v29, v0
	v_mov_b32_e32 v30, v0
	v_mov_b32_e32 v31, v0
	v_mov_b32_e32 v32, v0
	v_mov_b32_e32 v33, v0
	v_mov_b32_e32 v34, v0
	v_mov_b32_e32 v35, v0
	v_mov_b32_e32 v36, v0
	v_mov_b32_e32 v37, v0
	v_mov_b32_e32 v38, v0
	v_mov_b32_e32 v39, v0
	v_mov_b32_e32 v40, v0
	v_mov_b32_e32 v41, v0
	v_mov_b32_e32 v42, v0
	v_mov_b32_e32 v43, v0
	v_mov_b32_e32 v44, v0
	v_mov_b32_e32 v45, v0
	v_mov_b32_e32 v46, v0
	v_mov_b32_e32 v47, v0
	v_mov_b32_e32 v48, v0
	v_mov_b32_e32 v49, v0
	v_mov_b32_e32 v50, v0
	v_mov_b32_e32 v51, v0
	v_mov_b32_e32 v52, v0
	v_mov_b32_e32 v53, v0
	v_mov_b32_e32 v54, v0
	v_mov_b32_e32 v55, v0
	v_mov_b32_e32 v56, v0
	v_mov_b32_e32 v57, v0
	v_mov_b32_e32 v58, v0
	v_mov_b32_e32 v59, v0
	v_mov_b32_e32 v60, v0
	v_mov_b32_e32 v61, v0
	v_mov_b32_e32 v62, v0
	v_mov_b32_e32 v63, v0
	s_branch .LBB0_109
